# merge: LDS-DMA in saddr form (no VGPR address temporaries), fragment address registers re-materialised, epilogue private registers inside fragment quads -> all 16 merged blocks resident (13 registers
# speedup vs baseline: 1.0079x; 1.0079x over previous
.LBB0_1018:
	s_ashr_i32 s15, s14, 31
	s_ashr_i32 s13, s12, 31
	s_lshl_b64 s[16:17], s[14:15], 19
	s_lshl_b64 s[18:19], s[12:13], 9
	s_add_u32 s13, s34, s16
	s_addc_u32 s15, s35, s17
	s_add_u32 s16, s13, s18
	s_addc_u32 s17, s15, s19
	s_and_b64 s[18:19], s[2:3], exec
	s_cselect_b32 s29, s17, s23
	s_cselect_b32 s28, s16, s22
	s_lshl_b32 s13, s12, 2
	s_add_i32 s18, s13, s51
	s_ashr_i32 s19, s18, 31
	s_lshl_b64 s[18:19], s[18:19], 17
	s_add_u32 s18, s36, s18
	s_addc_u32 s19, s37, s19
	s_and_b64 s[26:27], s[2:3], exec
	s_cselect_b32 s27, s19, s25
	s_cselect_b32 s26, s18, s24
	s_add_i32 s15, 0, 0x10000
	s_add_i32 s21, 0, 0x14000
	v_add_u32_e32 v253, 0x10000, v174
	v_add_u32_e32 v252, 0x14000, v174
	ds_read_b128 v[128:131], v253
	ds_read_b128 v[132:135], v253 offset:1024
	ds_read_b128 v[136:139], v253 offset:2048
	ds_read_b128 v[140:143], v253 offset:3072
	ds_read_b128 v[144:147], v252
	ds_read_b128 v[148:151], v252 offset:1024
	ds_read_b128 v[152:155], v252 offset:2048
	ds_read_b128 v[156:159], v252 offset:3072
	s_add_u32 s52, s22, 0x40080
	s_addc_u32 s53, s23, 0
	s_add_i32 s55, s39, 0xc000
	s_waitcnt vmcnt(0)
	s_mov_b32 m0, s55
	s_add_i32 s13, s39, 0xe000
	ds_read_b128 v[168:171], v175
	ds_read_b128 v[176:179], v175 offset:1024
	ds_read_b128 v[180:183], v175 offset:2048
	ds_read_b128 v[184:187], v175 offset:3072
	ds_read_b128 v[188:191], v175 offset:4096
	ds_read_b128 v[192:195], v175 offset:5120
	ds_read_b128 v[196:199], v175 offset:6144
	ds_read_b128 v[200:203], v175 offset:7168
	global_load_lds_dwordx4 v160, s[52:53]
	s_mov_b32 m0, s13
	s_nop 0
	global_load_lds_dwordx4 v162, s[52:53]
	s_waitcnt vmcnt(8)
	s_waitcnt lgkmcnt(0)
	s_barrier
	s_setprio 1
	s_waitcnt lgkmcnt(0)
	v_mfma_f32_16x16x32_bf16 v[0:3], v[128:131], v[168:171], 0
	v_mfma_f32_16x16x32_bf16 v[4:7], v[136:139], v[168:171], 0
	v_mfma_f32_16x16x32_bf16 v[16:19], v[128:131], v[180:183], 0
	v_mfma_f32_16x16x32_bf16 v[20:23], v[136:139], v[180:183], 0
	v_mfma_f32_16x16x32_bf16 v[32:35], v[128:131], v[188:191], 0
	v_mfma_f32_16x16x32_bf16 v[36:39], v[136:139], v[188:191], 0
	v_mfma_f32_16x16x32_bf16 v[48:51], v[128:131], v[196:199], 0
	v_mfma_f32_16x16x32_bf16 v[52:55], v[136:139], v[196:199], 0
	v_mfma_f32_16x16x32_bf16 v[0:3], v[132:135], v[176:179], v[0:3]
	v_mfma_f32_16x16x32_bf16 v[4:7], v[140:143], v[176:179], v[4:7]
	v_mfma_f32_16x16x32_bf16 v[16:19], v[132:135], v[184:187], v[16:19]
	v_mfma_f32_16x16x32_bf16 v[20:23], v[140:143], v[184:187], v[20:23]
	v_mfma_f32_16x16x32_bf16 v[32:35], v[132:135], v[192:195], v[32:35]
	v_mfma_f32_16x16x32_bf16 v[36:39], v[140:143], v[192:195], v[36:39]
	v_mfma_f32_16x16x32_bf16 v[48:51], v[132:135], v[200:203], v[48:51]
	v_mfma_f32_16x16x32_bf16 v[52:55], v[140:143], v[200:203], v[52:55]
	s_setprio 0
	s_setprio 1
	v_mfma_f32_16x16x32_bf16 v[8:11], v[144:147], v[168:171], 0
	v_mfma_f32_16x16x32_bf16 v[12:15], v[152:155], v[168:171], 0
	v_mfma_f32_16x16x32_bf16 v[8:11], v[148:151], v[176:179], v[8:11]
	v_mfma_f32_16x16x32_bf16 v[12:15], v[156:159], v[176:179], v[12:15]
	v_mfma_f32_16x16x32_bf16 v[24:27], v[144:147], v[180:183], 0
	v_mfma_f32_16x16x32_bf16 v[28:31], v[152:155], v[180:183], 0
	v_mfma_f32_16x16x32_bf16 v[24:27], v[148:151], v[184:187], v[24:27]
	v_mfma_f32_16x16x32_bf16 v[28:31], v[156:159], v[184:187], v[28:31]
	v_mfma_f32_16x16x32_bf16 v[40:43], v[144:147], v[188:191], 0
	v_mfma_f32_16x16x32_bf16 v[44:47], v[152:155], v[188:191], 0
	v_mfma_f32_16x16x32_bf16 v[40:43], v[148:151], v[192:195], v[40:43]
	v_mfma_f32_16x16x32_bf16 v[44:47], v[156:159], v[192:195], v[44:47]
	v_mfma_f32_16x16x32_bf16 v[56:59], v[144:147], v[196:199], 0
	v_mfma_f32_16x16x32_bf16 v[60:63], v[152:155], v[196:199], 0
	v_mfma_f32_16x16x32_bf16 v[56:59], v[148:151], v[200:203], v[56:59]
	v_mfma_f32_16x16x32_bf16 v[60:63], v[156:159], v[200:203], v[60:63]
	s_setprio 0
	s_barrier
	s_add_i32 s53, s15, s38
	s_mov_b64 s[58:59], 0x100
	s_add_i32 s15, s53, 0x2000
	s_add_u32 s68, s24, s58
	s_addc_u32 s69, s25, s59
	s_mov_b32 m0, s53
	s_add_u32 s70, s24, s58
	s_addc_u32 s71, s25, s59
	s_add_u32 s56, s24, 0x10100
	ds_read_b128 v[168:171], v175 offset:16384
	ds_read_b128 v[176:179], v175 offset:17408
	ds_read_b128 v[180:183], v175 offset:18432
	ds_read_b128 v[184:187], v175 offset:19456
	ds_read_b128 v[188:191], v175 offset:20480
	ds_read_b128 v[192:195], v175 offset:21504
	ds_read_b128 v[196:199], v175 offset:22528
	ds_read_b128 v[200:203], v175 offset:23552
	global_load_lds_dwordx4 v232, s[68:69]
	s_mov_b32 m0, s15
	s_addc_u32 s57, s25, 0
	s_add_i32 s21, s21, s38
	global_load_lds_dwordx4 v164, s[70:71]
	s_mov_b32 m0, s21
	s_add_i32 s52, s21, 0x2000
	global_load_lds_dwordx4 v232, s[56:57]
	s_mov_b32 m0, s52
	global_load_lds_dwordx4 v164, s[56:57]
	s_add_u32 s68, s22, s58
	s_addc_u32 s69, s23, s59
	s_mov_b32 m0, s39
	global_load_lds_dwordx4 v160, s[68:69]
	s_add_u32 s68, s22, s58
	s_addc_u32 s69, s23, s59
	s_mov_b32 m0, s40
	s_nop 0
	global_load_lds_dwordx4 v162, s[68:69]
	s_waitcnt vmcnt(8)
	s_waitcnt lgkmcnt(0)
	s_barrier
	s_setprio 1
	s_waitcnt lgkmcnt(0)
	v_mfma_f32_16x16x32_bf16 v[64:67], v[128:131], v[168:171], 0
	v_mfma_f32_16x16x32_bf16 v[80:83], v[128:131], v[180:183], 0
	v_mfma_f32_16x16x32_bf16 v[96:99], v[128:131], v[188:191], 0
	v_mfma_f32_16x16x32_bf16 v[112:115], v[128:131], v[196:199], 0
	v_mfma_f32_16x16x32_bf16 v[64:67], v[132:135], v[176:179], v[64:67]
	v_mfma_f32_16x16x32_bf16 v[68:71], v[136:139], v[168:171], 0
	v_mfma_f32_16x16x32_bf16 v[80:83], v[132:135], v[184:187], v[80:83]
	v_mfma_f32_16x16x32_bf16 v[84:87], v[136:139], v[180:183], 0
	v_mfma_f32_16x16x32_bf16 v[96:99], v[132:135], v[192:195], v[96:99]
	v_mfma_f32_16x16x32_bf16 v[112:115], v[132:135], v[200:203], v[112:115]
	v_mfma_f32_16x16x32_bf16 v[116:119], v[136:139], v[196:199], 0
	v_mfma_f32_16x16x32_bf16 v[68:71], v[140:143], v[176:179], v[68:71]
	v_mfma_f32_16x16x32_bf16 v[84:87], v[140:143], v[184:187], v[84:87]
	v_mfma_f32_16x16x32_bf16 v[100:103], v[136:139], v[188:191], 0
	v_mfma_f32_16x16x32_bf16 v[116:119], v[140:143], v[200:203], v[116:119]
	v_mfma_f32_16x16x32_bf16 v[100:103], v[140:143], v[192:195], v[100:103]
	s_setprio 0
	s_setprio 1
	v_mfma_f32_16x16x32_bf16 v[72:75], v[144:147], v[168:171], 0
	v_mfma_f32_16x16x32_bf16 v[76:79], v[152:155], v[168:171], 0
	v_mfma_f32_16x16x32_bf16 v[72:75], v[148:151], v[176:179], v[72:75]
	v_mfma_f32_16x16x32_bf16 v[76:79], v[156:159], v[176:179], v[76:79]
	v_mfma_f32_16x16x32_bf16 v[88:91], v[144:147], v[180:183], 0
	v_mfma_f32_16x16x32_bf16 v[92:95], v[152:155], v[180:183], 0
	v_mfma_f32_16x16x32_bf16 v[104:107], v[144:147], v[188:191], 0
	v_mfma_f32_16x16x32_bf16 v[120:123], v[144:147], v[196:199], 0
	v_mfma_f32_16x16x32_bf16 v[88:91], v[148:151], v[184:187], v[88:91]
	v_mfma_f32_16x16x32_bf16 v[92:95], v[156:159], v[184:187], v[92:95]
	v_mfma_f32_16x16x32_bf16 v[104:107], v[148:151], v[192:195], v[104:107]
	v_mfma_f32_16x16x32_bf16 v[108:111], v[152:155], v[188:191], 0
	v_mfma_f32_16x16x32_bf16 v[120:123], v[148:151], v[200:203], v[120:123]
	v_mfma_f32_16x16x32_bf16 v[124:127], v[152:155], v[196:199], 0
	v_mfma_f32_16x16x32_bf16 v[108:111], v[156:159], v[192:195], v[108:111]
	v_mfma_f32_16x16x32_bf16 v[124:127], v[156:159], v[200:203], v[124:127]
	s_setprio 0
	s_barrier
	s_add_i32 s54, 0, 0x18000
	s_add_i32 s60, 0, 0x1c000
	v_add_u32_e32 v253, 0x18000, v174
	v_add_u32_e32 v252, 0x1c000, v174
	ds_read_b128 v[128:131], v253
	ds_read_b128 v[132:135], v253 offset:1024
	ds_read_b128 v[136:139], v253 offset:2048
	ds_read_b128 v[140:143], v253 offset:3072
	ds_read_b128 v[144:147], v252
	ds_read_b128 v[148:151], v252 offset:1024
	ds_read_b128 v[152:155], v252 offset:2048
	ds_read_b128 v[156:159], v252 offset:3072
	s_add_u32 s56, s22, 0x40100
	s_addc_u32 s57, s23, 0
	s_mov_b32 m0, s41
	ds_read_b128 v[168:171], v175 offset:32768
	ds_read_b128 v[176:179], v175 offset:33792
	ds_read_b128 v[180:183], v175 offset:34816
	ds_read_b128 v[184:187], v175 offset:35840
	ds_read_b128 v[188:191], v175 offset:36864
	ds_read_b128 v[192:195], v175 offset:37888
	ds_read_b128 v[196:199], v175 offset:38912
	ds_read_b128 v[200:203], v175 offset:39936
	global_load_lds_dwordx4 v160, s[56:57]
	s_mov_b32 m0, s42
	s_nop 0
	global_load_lds_dwordx4 v162, s[56:57]
	s_waitcnt vmcnt(8)
	s_waitcnt lgkmcnt(0)
	s_barrier
	s_setprio 1
	s_waitcnt lgkmcnt(0)
	v_mfma_f32_16x16x32_bf16 v[0:3], v[128:131], v[168:171], v[0:3]
	v_mfma_f32_16x16x32_bf16 v[4:7], v[136:139], v[168:171], v[4:7]
	v_mfma_f32_16x16x32_bf16 v[16:19], v[128:131], v[180:183], v[16:19]
	v_mfma_f32_16x16x32_bf16 v[20:23], v[136:139], v[180:183], v[20:23]
	v_mfma_f32_16x16x32_bf16 v[32:35], v[128:131], v[188:191], v[32:35]
	v_mfma_f32_16x16x32_bf16 v[36:39], v[136:139], v[188:191], v[36:39]
	v_mfma_f32_16x16x32_bf16 v[48:51], v[128:131], v[196:199], v[48:51]
	v_mfma_f32_16x16x32_bf16 v[52:55], v[136:139], v[196:199], v[52:55]
	v_mfma_f32_16x16x32_bf16 v[0:3], v[132:135], v[176:179], v[0:3]
	v_mfma_f32_16x16x32_bf16 v[4:7], v[140:143], v[176:179], v[4:7]
	v_mfma_f32_16x16x32_bf16 v[16:19], v[132:135], v[184:187], v[16:19]
	v_mfma_f32_16x16x32_bf16 v[20:23], v[140:143], v[184:187], v[20:23]
	v_mfma_f32_16x16x32_bf16 v[32:35], v[132:135], v[192:195], v[32:35]
	v_mfma_f32_16x16x32_bf16 v[36:39], v[140:143], v[192:195], v[36:39]
	v_mfma_f32_16x16x32_bf16 v[48:51], v[132:135], v[200:203], v[48:51]
	v_mfma_f32_16x16x32_bf16 v[52:55], v[140:143], v[200:203], v[52:55]
	s_setprio 0
	s_setprio 1
	v_mfma_f32_16x16x32_bf16 v[8:11], v[144:147], v[168:171], v[8:11]
	v_mfma_f32_16x16x32_bf16 v[24:27], v[144:147], v[180:183], v[24:27]
	v_mfma_f32_16x16x32_bf16 v[28:31], v[152:155], v[180:183], v[28:31]
	v_mfma_f32_16x16x32_bf16 v[44:47], v[152:155], v[188:191], v[44:47]
	v_mfma_f32_16x16x32_bf16 v[56:59], v[144:147], v[196:199], v[56:59]
	v_mfma_f32_16x16x32_bf16 v[60:63], v[152:155], v[196:199], v[60:63]
	v_mfma_f32_16x16x32_bf16 v[8:11], v[148:151], v[176:179], v[8:11]
	v_mfma_f32_16x16x32_bf16 v[12:15], v[152:155], v[168:171], v[12:15]
	v_mfma_f32_16x16x32_bf16 v[24:27], v[148:151], v[184:187], v[24:27]
	v_mfma_f32_16x16x32_bf16 v[28:31], v[156:159], v[184:187], v[28:31]
	v_mfma_f32_16x16x32_bf16 v[40:43], v[144:147], v[188:191], v[40:43]
	v_mfma_f32_16x16x32_bf16 v[44:47], v[156:159], v[192:195], v[44:47]
	v_mfma_f32_16x16x32_bf16 v[56:59], v[148:151], v[200:203], v[56:59]
	v_mfma_f32_16x16x32_bf16 v[60:63], v[156:159], v[200:203], v[60:63]
	v_mfma_f32_16x16x32_bf16 v[12:15], v[156:159], v[176:179], v[12:15]
	v_mfma_f32_16x16x32_bf16 v[40:43], v[148:151], v[192:195], v[40:43]
	s_setprio 0
	s_barrier
	s_add_i32 s56, s54, s38
	s_mov_b64 s[62:63], 0x180
	s_add_i32 s54, s56, 0x2000
	s_add_u32 s68, s24, s62
	s_addc_u32 s69, s25, s63
	s_mov_b32 m0, s56
	s_add_u32 s70, s24, s62
	s_addc_u32 s71, s25, s63
	s_add_u32 s58, s24, 0x10180
	ds_read_b128 v[168:171], v175 offset:49152
	ds_read_b128 v[176:179], v175 offset:50176
	ds_read_b128 v[180:183], v175 offset:51200
	ds_read_b128 v[184:187], v175 offset:52224
	ds_read_b128 v[188:191], v175 offset:53248
	ds_read_b128 v[192:195], v175 offset:54272
	ds_read_b128 v[196:199], v175 offset:55296
	ds_read_b128 v[200:203], v175 offset:56320
	global_load_lds_dwordx4 v232, s[68:69]
	s_mov_b32 m0, s54
	s_addc_u32 s59, s25, 0
	s_add_i32 s24, s60, s38
	global_load_lds_dwordx4 v164, s[70:71]
	s_mov_b32 m0, s24
	s_add_i32 s25, s24, 0x2000
	global_load_lds_dwordx4 v232, s[58:59]
	s_mov_b32 m0, s25
	s_nop 0
	global_load_lds_dwordx4 v164, s[58:59]
	s_add_u32 s68, s22, s62
	s_addc_u32 s69, s23, s63
	s_mov_b32 m0, s47
	s_nop 0
	global_load_lds_dwordx4 v160, s[68:69]
	s_add_u32 s68, s22, s62
	s_addc_u32 s69, s23, s63
	s_mov_b32 m0, s48
	s_nop 0
	global_load_lds_dwordx4 v162, s[68:69]
	s_waitcnt vmcnt(8)
	s_waitcnt lgkmcnt(0)
	s_barrier
	s_setprio 1
	s_waitcnt lgkmcnt(0)
	v_mfma_f32_16x16x32_bf16 v[64:67], v[128:131], v[168:171], v[64:67]
	v_mfma_f32_16x16x32_bf16 v[68:71], v[136:139], v[168:171], v[68:71]
	v_mfma_f32_16x16x32_bf16 v[84:87], v[136:139], v[180:183], v[84:87]
	v_mfma_f32_16x16x32_bf16 v[96:99], v[128:131], v[188:191], v[96:99]
	v_mfma_f32_16x16x32_bf16 v[112:115], v[128:131], v[196:199], v[112:115]
	v_mfma_f32_16x16x32_bf16 v[116:119], v[136:139], v[196:199], v[116:119]
	v_mfma_f32_16x16x32_bf16 v[64:67], v[132:135], v[176:179], v[64:67]
	v_mfma_f32_16x16x32_bf16 v[68:71], v[140:143], v[176:179], v[68:71]
	v_mfma_f32_16x16x32_bf16 v[80:83], v[128:131], v[180:183], v[80:83]
	v_mfma_f32_16x16x32_bf16 v[84:87], v[140:143], v[184:187], v[84:87]
	v_mfma_f32_16x16x32_bf16 v[96:99], v[132:135], v[192:195], v[96:99]
	v_mfma_f32_16x16x32_bf16 v[100:103], v[136:139], v[188:191], v[100:103]
	v_mfma_f32_16x16x32_bf16 v[112:115], v[132:135], v[200:203], v[112:115]
	v_mfma_f32_16x16x32_bf16 v[116:119], v[140:143], v[200:203], v[116:119]
	v_mfma_f32_16x16x32_bf16 v[80:83], v[132:135], v[184:187], v[80:83]
	v_mfma_f32_16x16x32_bf16 v[100:103], v[140:143], v[192:195], v[100:103]
	s_setprio 0
	s_setprio 1
	v_mfma_f32_16x16x32_bf16 v[72:75], v[144:147], v[168:171], v[72:75]
	v_mfma_f32_16x16x32_bf16 v[76:79], v[152:155], v[168:171], v[76:79]
	v_mfma_f32_16x16x32_bf16 v[88:91], v[144:147], v[180:183], v[88:91]
	v_mfma_f32_16x16x32_bf16 v[92:95], v[152:155], v[180:183], v[92:95]
	v_mfma_f32_16x16x32_bf16 v[104:107], v[144:147], v[188:191], v[104:107]
	v_mfma_f32_16x16x32_bf16 v[108:111], v[152:155], v[188:191], v[108:111]
	v_mfma_f32_16x16x32_bf16 v[124:127], v[152:155], v[196:199], v[124:127]
	v_mfma_f32_16x16x32_bf16 v[72:75], v[148:151], v[176:179], v[72:75]
	v_mfma_f32_16x16x32_bf16 v[76:79], v[156:159], v[176:179], v[76:79]
	v_mfma_f32_16x16x32_bf16 v[92:95], v[156:159], v[184:187], v[92:95]
	v_mfma_f32_16x16x32_bf16 v[104:107], v[148:151], v[192:195], v[104:107]
	v_mfma_f32_16x16x32_bf16 v[108:111], v[156:159], v[192:195], v[108:111]
	v_mfma_f32_16x16x32_bf16 v[120:123], v[144:147], v[196:199], v[120:123]
	v_mfma_f32_16x16x32_bf16 v[124:127], v[156:159], v[200:203], v[124:127]
	v_mfma_f32_16x16x32_bf16 v[88:91], v[148:151], v[184:187], v[88:91]
	v_mfma_f32_16x16x32_bf16 v[120:123], v[148:151], v[200:203], v[120:123]
	s_setprio 0
	s_barrier
	v_add_u32_e32 v253, 0x10000, v174
	ds_read_b128 v[128:131], v253
	ds_read_b128 v[132:135], v253 offset:1024
	ds_read_b128 v[136:139], v253 offset:2048
	ds_read_b128 v[140:143], v253 offset:3072
	v_add_u32_e32 v253, 0x14000, v174
	ds_read_b128 v[144:147], v253
	ds_read_b128 v[148:151], v253 offset:1024
	ds_read_b128 v[152:155], v253 offset:2048
	ds_read_b128 v[156:159], v253 offset:3072
	s_add_u32 s22, s22, 0x40180
	s_addc_u32 s23, s23, 0
	s_mov_b32 m0, s55
	ds_read_b128 v[168:171], v175
	ds_read_b128 v[176:179], v175 offset:1024
	ds_read_b128 v[180:183], v175 offset:2048
	ds_read_b128 v[184:187], v175 offset:3072
	ds_read_b128 v[188:191], v175 offset:4096
	ds_read_b128 v[192:195], v175 offset:5120
	ds_read_b128 v[196:199], v175 offset:6144
	ds_read_b128 v[200:203], v175 offset:7168
	global_load_lds_dwordx4 v160, s[22:23]
	s_mov_b32 m0, s13
	s_nop 0
	global_load_lds_dwordx4 v162, s[22:23]
	s_waitcnt vmcnt(8)
	s_waitcnt lgkmcnt(0)
	s_barrier
	s_setprio 1
	s_waitcnt lgkmcnt(0)
	v_mfma_f32_16x16x32_bf16 v[0:3], v[128:131], v[168:171], v[0:3]
	v_mfma_f32_16x16x32_bf16 v[4:7], v[136:139], v[168:171], v[4:7]
	v_mfma_f32_16x16x32_bf16 v[16:19], v[128:131], v[180:183], v[16:19]
	v_mfma_f32_16x16x32_bf16 v[20:23], v[136:139], v[180:183], v[20:23]
	v_mfma_f32_16x16x32_bf16 v[32:35], v[128:131], v[188:191], v[32:35]
	v_mfma_f32_16x16x32_bf16 v[36:39], v[136:139], v[188:191], v[36:39]
	v_mfma_f32_16x16x32_bf16 v[48:51], v[128:131], v[196:199], v[48:51]
	v_mfma_f32_16x16x32_bf16 v[0:3], v[132:135], v[176:179], v[0:3]
	v_mfma_f32_16x16x32_bf16 v[4:7], v[140:143], v[176:179], v[4:7]
	v_mfma_f32_16x16x32_bf16 v[16:19], v[132:135], v[184:187], v[16:19]
	v_mfma_f32_16x16x32_bf16 v[20:23], v[140:143], v[184:187], v[20:23]
	v_mfma_f32_16x16x32_bf16 v[32:35], v[132:135], v[192:195], v[32:35]
	v_mfma_f32_16x16x32_bf16 v[36:39], v[140:143], v[192:195], v[36:39]
	v_mfma_f32_16x16x32_bf16 v[48:51], v[132:135], v[200:203], v[48:51]
	v_mfma_f32_16x16x32_bf16 v[52:55], v[136:139], v[196:199], v[52:55]
	v_mfma_f32_16x16x32_bf16 v[52:55], v[140:143], v[200:203], v[52:55]
	s_setprio 0
	s_setprio 1
	v_mfma_f32_16x16x32_bf16 v[8:11], v[144:147], v[168:171], v[8:11]
	v_mfma_f32_16x16x32_bf16 v[24:27], v[144:147], v[180:183], v[24:27]
	v_mfma_f32_16x16x32_bf16 v[28:31], v[152:155], v[180:183], v[28:31]
	v_mfma_f32_16x16x32_bf16 v[44:47], v[152:155], v[188:191], v[44:47]
	v_mfma_f32_16x16x32_bf16 v[56:59], v[144:147], v[196:199], v[56:59]
	v_mfma_f32_16x16x32_bf16 v[60:63], v[152:155], v[196:199], v[60:63]
	v_mfma_f32_16x16x32_bf16 v[8:11], v[148:151], v[176:179], v[8:11]
	v_mfma_f32_16x16x32_bf16 v[12:15], v[152:155], v[168:171], v[12:15]
	v_mfma_f32_16x16x32_bf16 v[24:27], v[148:151], v[184:187], v[24:27]
	v_mfma_f32_16x16x32_bf16 v[28:31], v[156:159], v[184:187], v[28:31]
	v_mfma_f32_16x16x32_bf16 v[40:43], v[144:147], v[188:191], v[40:43]
	v_mfma_f32_16x16x32_bf16 v[44:47], v[156:159], v[192:195], v[44:47]
	v_mfma_f32_16x16x32_bf16 v[56:59], v[148:151], v[200:203], v[56:59]
	v_mfma_f32_16x16x32_bf16 v[60:63], v[156:159], v[200:203], v[60:63]
	v_mfma_f32_16x16x32_bf16 v[12:15], v[156:159], v[176:179], v[12:15]
	v_mfma_f32_16x16x32_bf16 v[40:43], v[148:151], v[192:195], v[40:43]
	s_setprio 0
	s_barrier
	s_mov_b32 m0, s53
	s_add_u32 s22, s26, 0x10000
	ds_read_b128 v[168:171], v175 offset:16384
	ds_read_b128 v[176:179], v175 offset:17408
	ds_read_b128 v[180:183], v175 offset:18432
	ds_read_b128 v[184:187], v175 offset:19456
	ds_read_b128 v[188:191], v175 offset:20480
	ds_read_b128 v[192:195], v175 offset:21504
	ds_read_b128 v[196:199], v175 offset:22528
	ds_read_b128 v[200:203], v175 offset:23552
	global_load_lds_dwordx4 v232, s[26:27]
	s_mov_b32 m0, s15
	s_addc_u32 s23, s27, 0
	global_load_lds_dwordx4 v164, s[26:27]
	s_mov_b32 m0, s21
	s_nop 0
	global_load_lds_dwordx4 v232, s[22:23]
	s_mov_b32 m0, s52
	s_nop 0
	global_load_lds_dwordx4 v164, s[22:23]
	s_mov_b32 m0, s39
	s_nop 0
	global_load_lds_dwordx4 v160, s[28:29]
	s_mov_b32 m0, s40
	s_nop 0
	global_load_lds_dwordx4 v162, s[28:29]
	s_waitcnt vmcnt(8)
	s_waitcnt lgkmcnt(0)
	s_barrier
	s_setprio 1
	s_waitcnt lgkmcnt(0)
	v_mfma_f32_16x16x32_bf16 v[64:67], v[128:131], v[168:171], v[64:67]
	v_mfma_f32_16x16x32_bf16 v[64:67], v[132:135], v[176:179], v[64:67]
	v_mfma_f32_16x16x32_bf16 v[68:71], v[136:139], v[168:171], v[68:71]
	v_mfma_f32_16x16x32_bf16 v[68:71], v[140:143], v[176:179], v[68:71]
	v_mfma_f32_16x16x32_bf16 v[80:83], v[128:131], v[180:183], v[80:83]
	v_mfma_f32_16x16x32_bf16 v[80:83], v[132:135], v[184:187], v[80:83]
	v_mfma_f32_16x16x32_bf16 v[84:87], v[136:139], v[180:183], v[84:87]
	v_mfma_f32_16x16x32_bf16 v[84:87], v[140:143], v[184:187], v[84:87]
	v_mfma_f32_16x16x32_bf16 v[96:99], v[128:131], v[188:191], v[96:99]
	v_mfma_f32_16x16x32_bf16 v[112:115], v[128:131], v[196:199], v[112:115]
	v_mfma_f32_16x16x32_bf16 v[116:119], v[136:139], v[196:199], v[116:119]
	v_mfma_f32_16x16x32_bf16 v[96:99], v[132:135], v[192:195], v[96:99]
	v_mfma_f32_16x16x32_bf16 v[100:103], v[136:139], v[188:191], v[100:103]
	v_mfma_f32_16x16x32_bf16 v[112:115], v[132:135], v[200:203], v[112:115]
	v_mfma_f32_16x16x32_bf16 v[116:119], v[140:143], v[200:203], v[116:119]
	v_mfma_f32_16x16x32_bf16 v[100:103], v[140:143], v[192:195], v[100:103]
	s_setprio 0
	s_setprio 1
	v_mfma_f32_16x16x32_bf16 v[72:75], v[144:147], v[168:171], v[72:75]
	v_mfma_f32_16x16x32_bf16 v[72:75], v[148:151], v[176:179], v[72:75]
	v_mfma_f32_16x16x32_bf16 v[76:79], v[152:155], v[168:171], v[76:79]
	v_mfma_f32_16x16x32_bf16 v[76:79], v[156:159], v[176:179], v[76:79]
	v_mfma_f32_16x16x32_bf16 v[88:91], v[144:147], v[180:183], v[88:91]
	v_mfma_f32_16x16x32_bf16 v[88:91], v[148:151], v[184:187], v[88:91]
	v_mfma_f32_16x16x32_bf16 v[92:95], v[152:155], v[180:183], v[92:95]
	v_mfma_f32_16x16x32_bf16 v[92:95], v[156:159], v[184:187], v[92:95]
	v_mfma_f32_16x16x32_bf16 v[104:107], v[144:147], v[188:191], v[104:107]
	v_mfma_f32_16x16x32_bf16 v[104:107], v[148:151], v[192:195], v[104:107]
	v_mfma_f32_16x16x32_bf16 v[108:111], v[152:155], v[188:191], v[108:111]
	v_mfma_f32_16x16x32_bf16 v[108:111], v[156:159], v[192:195], v[108:111]
	v_mfma_f32_16x16x32_bf16 v[120:123], v[144:147], v[196:199], v[120:123]
	v_mfma_f32_16x16x32_bf16 v[120:123], v[148:151], v[200:203], v[120:123]
	v_mfma_f32_16x16x32_bf16 v[124:127], v[152:155], v[196:199], v[124:127]
	v_mfma_f32_16x16x32_bf16 v[124:127], v[156:159], v[200:203], v[124:127]
	s_setprio 0
	s_barrier
	s_nop 4
	v_add_u32_e32 v253, 0x18000, v174
	ds_read_b128 v[128:131], v253
	ds_read_b128 v[132:135], v253 offset:1024
	ds_read_b128 v[136:139], v253 offset:2048
	ds_read_b128 v[140:143], v253 offset:3072
	v_add_u32_e32 v253, 0x1c000, v174
	ds_read_b128 v[144:147], v253
	ds_read_b128 v[148:151], v253 offset:1024
	ds_read_b128 v[152:155], v253 offset:2048
	ds_read_b128 v[156:159], v253 offset:3072
	s_add_u32 s22, s28, 0x40000
	s_addc_u32 s23, s29, 0
	s_mov_b32 m0, s41
	ds_read_b128 v[168:171], v175 offset:32768
	ds_read_b128 v[176:179], v175 offset:33792
	ds_read_b128 v[180:183], v175 offset:34816
	ds_read_b128 v[184:187], v175 offset:35840
	ds_read_b128 v[188:191], v175 offset:36864
	ds_read_b128 v[192:195], v175 offset:37888
	ds_read_b128 v[196:199], v175 offset:38912
	ds_read_b128 v[200:203], v175 offset:39936
	global_load_lds_dwordx4 v160, s[22:23]
	s_mov_b32 m0, s42
	s_nop 0
	global_load_lds_dwordx4 v162, s[22:23]
	s_waitcnt vmcnt(8)
	s_waitcnt lgkmcnt(0)
	s_barrier
	s_setprio 1
	s_waitcnt lgkmcnt(0)
	v_mfma_f32_16x16x32_bf16 v[0:3], v[128:131], v[168:171], v[0:3]
	v_mfma_f32_16x16x32_bf16 v[0:3], v[132:135], v[176:179], v[0:3]
	v_mfma_f32_16x16x32_bf16 v[4:7], v[136:139], v[168:171], v[4:7]
	v_mfma_f32_16x16x32_bf16 v[4:7], v[140:143], v[176:179], v[4:7]
	v_mfma_f32_16x16x32_bf16 v[16:19], v[128:131], v[180:183], v[16:19]
	v_mfma_f32_16x16x32_bf16 v[16:19], v[132:135], v[184:187], v[16:19]
	v_mfma_f32_16x16x32_bf16 v[20:23], v[136:139], v[180:183], v[20:23]
	v_mfma_f32_16x16x32_bf16 v[20:23], v[140:143], v[184:187], v[20:23]
	v_mfma_f32_16x16x32_bf16 v[32:35], v[128:131], v[188:191], v[32:35]
	v_mfma_f32_16x16x32_bf16 v[32:35], v[132:135], v[192:195], v[32:35]
	v_mfma_f32_16x16x32_bf16 v[36:39], v[136:139], v[188:191], v[36:39]
	v_mfma_f32_16x16x32_bf16 v[36:39], v[140:143], v[192:195], v[36:39]
	v_mfma_f32_16x16x32_bf16 v[48:51], v[128:131], v[196:199], v[48:51]
	v_mfma_f32_16x16x32_bf16 v[48:51], v[132:135], v[200:203], v[48:51]
	v_mfma_f32_16x16x32_bf16 v[52:55], v[136:139], v[196:199], v[52:55]
	v_mfma_f32_16x16x32_bf16 v[52:55], v[140:143], v[200:203], v[52:55]
	s_setprio 0
	s_setprio 1
	v_mfma_f32_16x16x32_bf16 v[12:15], v[152:155], v[168:171], v[12:15]
	v_mfma_f32_16x16x32_bf16 v[12:15], v[156:159], v[176:179], v[12:15]
	v_mfma_f32_16x16x32_bf16 v[24:27], v[144:147], v[180:183], v[24:27]
	v_mfma_f32_16x16x32_bf16 v[24:27], v[148:151], v[184:187], v[24:27]
	v_mfma_f32_16x16x32_bf16 v[28:31], v[152:155], v[180:183], v[28:31]
	v_mfma_f32_16x16x32_bf16 v[8:11], v[144:147], v[168:171], v[8:11]
	v_mfma_f32_16x16x32_bf16 v[28:31], v[156:159], v[184:187], v[28:31]
	v_mfma_f32_16x16x32_bf16 v[40:43], v[144:147], v[188:191], v[40:43]
	v_mfma_f32_16x16x32_bf16 v[8:11], v[148:151], v[176:179], v[8:11]
	v_mfma_f32_16x16x32_bf16 v[40:43], v[148:151], v[192:195], v[40:43]
	v_mfma_f32_16x16x32_bf16 v[44:47], v[152:155], v[188:191], v[44:47]
	v_mfma_f32_16x16x32_bf16 v[44:47], v[156:159], v[192:195], v[44:47]
	v_mfma_f32_16x16x32_bf16 v[56:59], v[144:147], v[196:199], v[56:59]
	v_mfma_f32_16x16x32_bf16 v[56:59], v[148:151], v[200:203], v[56:59]
	v_mfma_f32_16x16x32_bf16 v[60:63], v[152:155], v[196:199], v[60:63]
	v_mfma_f32_16x16x32_bf16 v[60:63], v[156:159], v[200:203], v[60:63]
	s_setprio 0
	s_barrier
	s_mov_b32 m0, s56
	s_add_u32 s68, s26, s94
	s_addc_u32 s69, s27, s95
	s_add_u32 s70, s26, s94
	s_addc_u32 s71, s27, s95
	s_add_u32 s22, s26, 0x10080
	s_nop 1
	ds_read_b128 v[168:171], v175 offset:49152
	ds_read_b128 v[176:179], v175 offset:50176
	ds_read_b128 v[180:183], v175 offset:51200
	ds_read_b128 v[184:187], v175 offset:52224
	ds_read_b128 v[188:191], v175 offset:53248
	ds_read_b128 v[192:195], v175 offset:54272
	ds_read_b128 v[196:199], v175 offset:55296
	ds_read_b128 v[200:203], v175 offset:56320
	global_load_lds_dwordx4 v232, s[68:69]
	s_mov_b32 m0, s54
	s_addc_u32 s23, s27, 0
	global_load_lds_dwordx4 v164, s[70:71]
	s_mov_b32 m0, s24
	s_nop 0
	global_load_lds_dwordx4 v232, s[22:23]
	s_mov_b32 m0, s25
	s_nop 0
	global_load_lds_dwordx4 v164, s[22:23]
	s_add_u32 s68, s28, s94
	s_addc_u32 s69, s29, s95
	s_mov_b32 m0, s47
	s_nop 0
	global_load_lds_dwordx4 v160, s[68:69]
	s_add_u32 s68, s28, s94
	s_addc_u32 s69, s29, s95
	s_mov_b32 m0, s48
	s_nop 0
	global_load_lds_dwordx4 v162, s[68:69]
	s_waitcnt vmcnt(8)
	s_waitcnt lgkmcnt(0)
	s_barrier
	s_setprio 1
	s_waitcnt lgkmcnt(0)
	v_mfma_f32_16x16x32_bf16 v[64:67], v[128:131], v[168:171], v[64:67]
	v_mfma_f32_16x16x32_bf16 v[64:67], v[132:135], v[176:179], v[64:67]
	v_mfma_f32_16x16x32_bf16 v[68:71], v[136:139], v[168:171], v[68:71]
	v_mfma_f32_16x16x32_bf16 v[68:71], v[140:143], v[176:179], v[68:71]
	v_mfma_f32_16x16x32_bf16 v[80:83], v[128:131], v[180:183], v[80:83]
	v_mfma_f32_16x16x32_bf16 v[80:83], v[132:135], v[184:187], v[80:83]
	v_mfma_f32_16x16x32_bf16 v[84:87], v[136:139], v[180:183], v[84:87]
	v_mfma_f32_16x16x32_bf16 v[84:87], v[140:143], v[184:187], v[84:87]
	v_mfma_f32_16x16x32_bf16 v[96:99], v[128:131], v[188:191], v[96:99]
	v_mfma_f32_16x16x32_bf16 v[112:115], v[128:131], v[196:199], v[112:115]
	v_mfma_f32_16x16x32_bf16 v[96:99], v[132:135], v[192:195], v[96:99]
	v_mfma_f32_16x16x32_bf16 v[100:103], v[136:139], v[188:191], v[100:103]
	v_mfma_f32_16x16x32_bf16 v[112:115], v[132:135], v[200:203], v[112:115]
	v_mfma_f32_16x16x32_bf16 v[116:119], v[136:139], v[196:199], v[116:119]
	v_mfma_f32_16x16x32_bf16 v[100:103], v[140:143], v[192:195], v[100:103]
	v_mfma_f32_16x16x32_bf16 v[116:119], v[140:143], v[200:203], v[116:119]
	s_setprio 0
	s_setprio 1
	v_mfma_f32_16x16x32_bf16 v[72:75], v[144:147], v[168:171], v[72:75]
	v_mfma_f32_16x16x32_bf16 v[72:75], v[148:151], v[176:179], v[72:75]
	v_mfma_f32_16x16x32_bf16 v[76:79], v[152:155], v[168:171], v[76:79]
	v_mfma_f32_16x16x32_bf16 v[76:79], v[156:159], v[176:179], v[76:79]
	v_mfma_f32_16x16x32_bf16 v[88:91], v[144:147], v[180:183], v[88:91]
	v_mfma_f32_16x16x32_bf16 v[88:91], v[148:151], v[184:187], v[88:91]
	v_mfma_f32_16x16x32_bf16 v[92:95], v[152:155], v[180:183], v[92:95]
	v_mfma_f32_16x16x32_bf16 v[92:95], v[156:159], v[184:187], v[92:95]
	v_mfma_f32_16x16x32_bf16 v[104:107], v[144:147], v[188:191], v[104:107]
	v_mfma_f32_16x16x32_bf16 v[104:107], v[148:151], v[192:195], v[104:107]
	v_mfma_f32_16x16x32_bf16 v[108:111], v[152:155], v[188:191], v[108:111]
	v_mfma_f32_16x16x32_bf16 v[108:111], v[156:159], v[192:195], v[108:111]
	v_mfma_f32_16x16x32_bf16 v[120:123], v[144:147], v[196:199], v[120:123]
	v_mfma_f32_16x16x32_bf16 v[120:123], v[148:151], v[200:203], v[120:123]
	v_mfma_f32_16x16x32_bf16 v[124:127], v[152:155], v[196:199], v[124:127]
	v_mfma_f32_16x16x32_bf16 v[124:127], v[156:159], v[200:203], v[124:127]
	s_setprio 0
	s_barrier
	s_andn2_b64 vcc, exec, s[10:11]
	s_cbranch_vccnz .LBB0_1020
	s_barrier
.LBB0_1020:
	s_lshl_b32 s13, s20, 8
	s_lshl_b32 s20, s5, 10
	v_mbcnt_lo_u32_b32 v128, -1, 0
	v_mbcnt_hi_u32_b32 v128, -1, v128
	s_lshl_b32 s4, s4, 8
	v_and_or_b32 v190, v128, 15, s45
	s_ashr_i32 s21, s20, 31
	v_ashrrev_i32_e32 v128, 1, v128
	v_add_u32_e32 v186, s13, v190
	s_or_b32 s4, s4, s46
	s_lshl_b64 s[20:21], s[20:21], 1
	v_and_b32_e32 v128, -8, v128
	s_add_u32 s20, s43, s20
	v_ashrrev_i32_e32 v187, 31, v186
	v_add_u32_e32 v184, s4, v128
	s_addc_u32 s21, s44, s21
	v_lshlrev_b64 v[128:129], 13, v[186:187]
	v_lshl_add_u64 v[128:129], s[20:21], 0, v[128:129]
	v_ashrrev_i32_e32 v185, 31, v184
	v_lshl_add_u64 v[128:129], v[184:185], 1, v[128:129]
	v_lshlrev_b64 v[130:131], 11, v[186:187]
	v_lshl_add_u64 v[130:131], s[8:9], 0, v[130:131]
	v_lshl_add_u64 v[188:189], v[184:185], 1, v[130:131]
	v_mov_b64_e32 v[192:193], v[128:129]
	s_mov_b32 s59, 0
	s_waitcnt lgkmcnt(0)
	v_mbcnt_lo_u32_b32 v191, -1, 0
	v_mbcnt_hi_u32_b32 v191, -1, v191
	s_lshl_b32 s58, s45, 6
	s_lshl_b32 s59, s46, 5
	s_add_i32 s58, s58, s59
	s_add_i32 s58, s58, 0x21000
	s_mov_b32 s59, 0
	v_lshl_add_u32 v191, v191, 4, s58
	s_cmp_eq_u32 s5, 0
	s_cbranch_scc1 .Lmepi_z0
	s_cmp_eq_u32 s5, 3
	s_cbranch_scc1 .Lmepi_z3
	global_load_dwordx4 v[128:131], v[192:193], off nt
	global_load_dwordx4 v[132:135], v[192:193], off offset:256 nt
	s_mov_b32 s58, 0x20000
	v_lshl_add_u64 v[194:195], v[192:193], 0, s[58:59]
	global_load_dwordx4 v[136:139], v[194:195], off nt
	global_load_dwordx4 v[140:143], v[194:195], off offset:256 nt
	s_mov_b32 s58, 0x40000
	v_lshl_add_u64 v[196:197], v[192:193], 0, s[58:59]
	global_load_dwordx4 v[144:147], v[196:197], off nt
	global_load_dwordx4 v[148:151], v[196:197], off offset:256 nt
	s_mov_b32 s58, 0x60000
	v_lshl_add_u64 v[198:199], v[192:193], 0, s[58:59]
	global_load_dwordx4 v[152:155], v[198:199], off nt
	global_load_dwordx4 v[156:159], v[198:199], off offset:256 nt
	s_mov_b32 s58, 0x100000
	v_lshl_add_u64 v[200:201], v[192:193], 0, s[58:59]
	global_load_dwordx4 v[168:171], v[200:201], off nt
	global_load_dwordx4 v[176:179], v[200:201], off offset:256 nt
	s_waitcnt vmcnt(9)
	v_lshlrev_b32_e32 v202, 16, v128
	v_and_b32_e32 v203, 0xffff0000, v128
	v_pk_mul_f32 v[0:1], v[0:1], v[202:203]
	v_lshlrev_b32_e32 v194, 16, v129
	v_and_b32_e32 v195, 0xffff0000, v129
	v_pk_mul_f32 v[2:3], v[2:3], v[194:195]
	v_lshlrev_b32_e32 v196, 16, v130
	v_and_b32_e32 v197, 0xffff0000, v130
	v_pk_mul_f32 v[4:5], v[4:5], v[196:197]
	v_lshlrev_b32_e32 v198, 16, v131
	v_and_b32_e32 v199, 0xffff0000, v131
	v_pk_mul_f32 v[6:7], v[6:7], v[198:199]
	v_lshlrev_b32_e32 v200, 16, v204
	v_and_b32_e32 v201, 0xffff0000, v204
	v_pk_add_f32 v[0:1], v[0:1], v[200:201]
	v_lshlrev_b32_e32 v202, 16, v205
	v_and_b32_e32 v203, 0xffff0000, v205
	v_pk_add_f32 v[2:3], v[2:3], v[202:203]
	v_lshlrev_b32_e32 v194, 16, v206
	v_and_b32_e32 v195, 0xffff0000, v206
	v_pk_add_f32 v[4:5], v[4:5], v[194:195]
	v_lshlrev_b32_e32 v196, 16, v207
	v_and_b32_e32 v197, 0xffff0000, v207
	v_pk_add_f32 v[6:7], v[6:7], v[196:197]
	v_cvt_pk_bf16_f32 v204, v0, v1
	v_cvt_pk_bf16_f32 v205, v2, v3
	v_cvt_pk_bf16_f32 v206, v4, v5
	v_cvt_pk_bf16_f32 v207, v6, v7
	s_waitcnt vmcnt(8)
	v_lshlrev_b32_e32 v198, 16, v132
	v_and_b32_e32 v199, 0xffff0000, v132
	v_pk_mul_f32 v[8:9], v[8:9], v[198:199]
	v_lshlrev_b32_e32 v200, 16, v133
	v_and_b32_e32 v201, 0xffff0000, v133
	v_pk_mul_f32 v[10:11], v[10:11], v[200:201]
	v_lshlrev_b32_e32 v202, 16, v134
	v_and_b32_e32 v203, 0xffff0000, v134
	v_pk_mul_f32 v[12:13], v[12:13], v[202:203]
	v_lshlrev_b32_e32 v194, 16, v135
	v_and_b32_e32 v195, 0xffff0000, v135
	v_pk_mul_f32 v[14:15], v[14:15], v[194:195]
	v_lshlrev_b32_e32 v196, 16, v208
	v_and_b32_e32 v197, 0xffff0000, v208
	v_pk_add_f32 v[8:9], v[8:9], v[196:197]
	v_lshlrev_b32_e32 v198, 16, v209
	v_and_b32_e32 v199, 0xffff0000, v209
	v_pk_add_f32 v[10:11], v[10:11], v[198:199]
	v_lshlrev_b32_e32 v200, 16, v210
	v_and_b32_e32 v201, 0xffff0000, v210
	v_pk_add_f32 v[12:13], v[12:13], v[200:201]
	v_lshlrev_b32_e32 v202, 16, v211
	v_and_b32_e32 v203, 0xffff0000, v211
	v_pk_add_f32 v[14:15], v[14:15], v[202:203]
	v_cvt_pk_bf16_f32 v208, v8, v9
	v_cvt_pk_bf16_f32 v209, v10, v11
	v_cvt_pk_bf16_f32 v210, v12, v13
	v_cvt_pk_bf16_f32 v211, v14, v15
	s_mov_b32 s58, 0x120000
	v_lshl_add_u64 v[194:195], v[192:193], 0, s[58:59]
	global_load_dwordx4 v[180:183], v[194:195], off nt
	global_load_dwordx4 v[0:3], v[194:195], off offset:256 nt
	s_mov_b32 s58, 0x140000
	v_lshl_add_u64 v[196:197], v[192:193], 0, s[58:59]
	global_load_dwordx4 v[4:7], v[196:197], off nt
	global_load_dwordx4 v[128:131], v[196:197], off offset:256 nt
	ds_read_b128 v[8:11], v191 offset:0
	s_waitcnt vmcnt(11)
	v_lshlrev_b32_e32 v198, 16, v136
	v_and_b32_e32 v199, 0xffff0000, v136
	v_pk_mul_f32 v[16:17], v[16:17], v[198:199]
	v_lshlrev_b32_e32 v200, 16, v137
	v_and_b32_e32 v201, 0xffff0000, v137
	v_pk_mul_f32 v[18:19], v[18:19], v[200:201]
	v_lshlrev_b32_e32 v202, 16, v138
	v_and_b32_e32 v203, 0xffff0000, v138
	v_pk_mul_f32 v[20:21], v[20:21], v[202:203]
	v_lshlrev_b32_e32 v194, 16, v139
	v_and_b32_e32 v195, 0xffff0000, v139
	v_pk_mul_f32 v[22:23], v[22:23], v[194:195]
	v_lshlrev_b32_e32 v196, 16, v212
	v_and_b32_e32 v197, 0xffff0000, v212
	v_pk_add_f32 v[16:17], v[16:17], v[196:197]
	v_lshlrev_b32_e32 v198, 16, v213
	v_and_b32_e32 v199, 0xffff0000, v213
	v_pk_add_f32 v[18:19], v[18:19], v[198:199]
	v_lshlrev_b32_e32 v200, 16, v214
	v_and_b32_e32 v201, 0xffff0000, v214
	v_pk_add_f32 v[20:21], v[20:21], v[200:201]
	v_lshlrev_b32_e32 v202, 16, v215
	v_and_b32_e32 v203, 0xffff0000, v215
	v_pk_add_f32 v[22:23], v[22:23], v[202:203]
	v_cvt_pk_bf16_f32 v212, v16, v17
	v_cvt_pk_bf16_f32 v213, v18, v19
	v_cvt_pk_bf16_f32 v214, v20, v21
	v_cvt_pk_bf16_f32 v215, v22, v23
	s_waitcnt vmcnt(10)
	v_lshlrev_b32_e32 v194, 16, v140
	v_and_b32_e32 v195, 0xffff0000, v140
	v_pk_mul_f32 v[24:25], v[24:25], v[194:195]
	v_lshlrev_b32_e32 v196, 16, v141
	v_and_b32_e32 v197, 0xffff0000, v141
	v_pk_mul_f32 v[26:27], v[26:27], v[196:197]
	v_lshlrev_b32_e32 v198, 16, v142
	v_and_b32_e32 v199, 0xffff0000, v142
	v_pk_mul_f32 v[28:29], v[28:29], v[198:199]
	v_lshlrev_b32_e32 v200, 16, v143
	v_and_b32_e32 v201, 0xffff0000, v143
	v_pk_mul_f32 v[30:31], v[30:31], v[200:201]
	v_lshlrev_b32_e32 v202, 16, v216
	v_and_b32_e32 v203, 0xffff0000, v216
	v_pk_add_f32 v[24:25], v[24:25], v[202:203]
	v_lshlrev_b32_e32 v194, 16, v217
	v_and_b32_e32 v195, 0xffff0000, v217
	v_pk_add_f32 v[26:27], v[26:27], v[194:195]
	v_lshlrev_b32_e32 v196, 16, v218
	v_and_b32_e32 v197, 0xffff0000, v218
	v_pk_add_f32 v[28:29], v[28:29], v[196:197]
	v_lshlrev_b32_e32 v198, 16, v219
	v_and_b32_e32 v199, 0xffff0000, v219
	v_pk_add_f32 v[30:31], v[30:31], v[198:199]
	v_cvt_pk_bf16_f32 v216, v24, v25
	v_cvt_pk_bf16_f32 v217, v26, v27
	v_cvt_pk_bf16_f32 v218, v28, v29
	v_cvt_pk_bf16_f32 v219, v30, v31
	s_mov_b32 s58, 0x160000
	v_lshl_add_u64 v[200:201], v[192:193], 0, s[58:59]
	global_load_dwordx4 v[12:15], v[200:201], off nt
	global_load_dwordx4 v[132:135], v[200:201], off offset:256 nt
	ds_read_b128 v[16:19], v191 offset:8192
	ds_read_b128 v[20:23], v191 offset:16384
	s_waitcnt vmcnt(11)
	v_lshlrev_b32_e32 v202, 16, v144
	v_and_b32_e32 v203, 0xffff0000, v144
	v_pk_mul_f32 v[32:33], v[32:33], v[202:203]
	v_lshlrev_b32_e32 v194, 16, v145
	v_and_b32_e32 v195, 0xffff0000, v145
	v_pk_mul_f32 v[34:35], v[34:35], v[194:195]
	v_lshlrev_b32_e32 v196, 16, v146
	v_and_b32_e32 v197, 0xffff0000, v146
	v_pk_mul_f32 v[36:37], v[36:37], v[196:197]
	v_lshlrev_b32_e32 v198, 16, v147
	v_and_b32_e32 v199, 0xffff0000, v147
	v_pk_mul_f32 v[38:39], v[38:39], v[198:199]
	v_lshlrev_b32_e32 v200, 16, v220
	v_and_b32_e32 v201, 0xffff0000, v220
	v_pk_add_f32 v[32:33], v[32:33], v[200:201]
	v_lshlrev_b32_e32 v202, 16, v221
	v_and_b32_e32 v203, 0xffff0000, v221
	v_pk_add_f32 v[34:35], v[34:35], v[202:203]
	v_lshlrev_b32_e32 v194, 16, v222
	v_and_b32_e32 v195, 0xffff0000, v222
	v_pk_add_f32 v[36:37], v[36:37], v[194:195]
	v_lshlrev_b32_e32 v196, 16, v223
	v_and_b32_e32 v197, 0xffff0000, v223
	v_pk_add_f32 v[38:39], v[38:39], v[196:197]
	v_cvt_pk_bf16_f32 v220, v32, v33
	v_cvt_pk_bf16_f32 v221, v34, v35
	v_cvt_pk_bf16_f32 v222, v36, v37
	v_cvt_pk_bf16_f32 v223, v38, v39
	s_waitcnt vmcnt(10)
	v_lshlrev_b32_e32 v198, 16, v148
	v_and_b32_e32 v199, 0xffff0000, v148
	v_pk_mul_f32 v[40:41], v[40:41], v[198:199]
	v_lshlrev_b32_e32 v200, 16, v149
	v_and_b32_e32 v201, 0xffff0000, v149
	v_pk_mul_f32 v[42:43], v[42:43], v[200:201]
	v_lshlrev_b32_e32 v202, 16, v150
	v_and_b32_e32 v203, 0xffff0000, v150
	v_pk_mul_f32 v[44:45], v[44:45], v[202:203]
	v_lshlrev_b32_e32 v194, 16, v151
	v_and_b32_e32 v195, 0xffff0000, v151
	v_pk_mul_f32 v[46:47], v[46:47], v[194:195]
	v_lshlrev_b32_e32 v196, 16, v224
	v_and_b32_e32 v197, 0xffff0000, v224
	v_pk_add_f32 v[40:41], v[40:41], v[196:197]
	v_lshlrev_b32_e32 v198, 16, v225
	v_and_b32_e32 v199, 0xffff0000, v225
	v_pk_add_f32 v[42:43], v[42:43], v[198:199]
	v_lshlrev_b32_e32 v200, 16, v226
	v_and_b32_e32 v201, 0xffff0000, v226
	v_pk_add_f32 v[44:45], v[44:45], v[200:201]
	v_lshlrev_b32_e32 v202, 16, v227
	v_and_b32_e32 v203, 0xffff0000, v227
	v_pk_add_f32 v[46:47], v[46:47], v[202:203]
	v_cvt_pk_bf16_f32 v224, v40, v41
	v_cvt_pk_bf16_f32 v225, v42, v43
	v_cvt_pk_bf16_f32 v226, v44, v45
	v_cvt_pk_bf16_f32 v227, v46, v47
	s_waitcnt vmcnt(9)
	v_lshlrev_b32_e32 v194, 16, v152
	v_and_b32_e32 v195, 0xffff0000, v152
	v_pk_mul_f32 v[48:49], v[48:49], v[194:195]
	v_lshlrev_b32_e32 v196, 16, v153
	v_and_b32_e32 v197, 0xffff0000, v153
	v_pk_mul_f32 v[50:51], v[50:51], v[196:197]
	v_lshlrev_b32_e32 v198, 16, v154
	v_and_b32_e32 v199, 0xffff0000, v154
	v_pk_mul_f32 v[52:53], v[52:53], v[198:199]
	v_lshlrev_b32_e32 v200, 16, v155
	v_and_b32_e32 v201, 0xffff0000, v155
	v_pk_mul_f32 v[54:55], v[54:55], v[200:201]
	v_lshlrev_b32_e32 v202, 16, v228
	v_and_b32_e32 v203, 0xffff0000, v228
	v_pk_add_f32 v[48:49], v[48:49], v[202:203]
	v_lshlrev_b32_e32 v194, 16, v229
	v_and_b32_e32 v195, 0xffff0000, v229
	v_pk_add_f32 v[50:51], v[50:51], v[194:195]
	v_lshlrev_b32_e32 v196, 16, v230
	v_and_b32_e32 v197, 0xffff0000, v230
	v_pk_add_f32 v[52:53], v[52:53], v[196:197]
	v_lshlrev_b32_e32 v198, 16, v231
	v_and_b32_e32 v199, 0xffff0000, v231
	v_pk_add_f32 v[54:55], v[54:55], v[198:199]
	v_cvt_pk_bf16_f32 v228, v48, v49
	v_cvt_pk_bf16_f32 v229, v50, v51
	v_cvt_pk_bf16_f32 v230, v52, v53
	v_cvt_pk_bf16_f32 v231, v54, v55
	s_waitcnt vmcnt(8)
	v_lshlrev_b32_e32 v200, 16, v156
	v_and_b32_e32 v201, 0xffff0000, v156
	v_pk_mul_f32 v[56:57], v[56:57], v[200:201]
	v_lshlrev_b32_e32 v202, 16, v157
	v_and_b32_e32 v203, 0xffff0000, v157
	v_pk_mul_f32 v[58:59], v[58:59], v[202:203]
	v_lshlrev_b32_e32 v194, 16, v158
	v_and_b32_e32 v195, 0xffff0000, v158
	v_pk_mul_f32 v[60:61], v[60:61], v[194:195]
	v_lshlrev_b32_e32 v196, 16, v159
	v_and_b32_e32 v197, 0xffff0000, v159
	v_pk_mul_f32 v[62:63], v[62:63], v[196:197]
	v_lshlrev_b32_e32 v198, 16, v236
	v_and_b32_e32 v199, 0xffff0000, v236
	v_pk_add_f32 v[56:57], v[56:57], v[198:199]
	v_lshlrev_b32_e32 v200, 16, v237
	v_and_b32_e32 v201, 0xffff0000, v237
	v_pk_add_f32 v[58:59], v[58:59], v[200:201]
	v_lshlrev_b32_e32 v202, 16, v238
	v_and_b32_e32 v203, 0xffff0000, v238
	v_pk_add_f32 v[60:61], v[60:61], v[202:203]
	v_lshlrev_b32_e32 v194, 16, v239
	v_and_b32_e32 v195, 0xffff0000, v239
	v_pk_add_f32 v[62:63], v[62:63], v[194:195]
	v_cvt_pk_bf16_f32 v236, v56, v57
	v_cvt_pk_bf16_f32 v237, v58, v59
	v_cvt_pk_bf16_f32 v238, v60, v61
	v_cvt_pk_bf16_f32 v239, v62, v63
	s_waitcnt vmcnt(7)
	v_lshlrev_b32_e32 v196, 16, v168
	v_and_b32_e32 v197, 0xffff0000, v168
	v_pk_mul_f32 v[64:65], v[64:65], v[196:197]
	v_lshlrev_b32_e32 v198, 16, v169
	v_and_b32_e32 v199, 0xffff0000, v169
	v_pk_mul_f32 v[66:67], v[66:67], v[198:199]
	v_lshlrev_b32_e32 v200, 16, v170
	v_and_b32_e32 v201, 0xffff0000, v170
	v_pk_mul_f32 v[68:69], v[68:69], v[200:201]
	v_lshlrev_b32_e32 v202, 16, v171
	v_and_b32_e32 v203, 0xffff0000, v171
	v_pk_mul_f32 v[70:71], v[70:71], v[202:203]
	v_lshlrev_b32_e32 v194, 16, v240
	v_and_b32_e32 v195, 0xffff0000, v240
	v_pk_add_f32 v[64:65], v[64:65], v[194:195]
	v_lshlrev_b32_e32 v196, 16, v241
	v_and_b32_e32 v197, 0xffff0000, v241
	v_pk_add_f32 v[66:67], v[66:67], v[196:197]
	v_lshlrev_b32_e32 v198, 16, v242
	v_and_b32_e32 v199, 0xffff0000, v242
	v_pk_add_f32 v[68:69], v[68:69], v[198:199]
	v_lshlrev_b32_e32 v200, 16, v243
	v_and_b32_e32 v201, 0xffff0000, v243
	v_pk_add_f32 v[70:71], v[70:71], v[200:201]
	v_cvt_pk_bf16_f32 v240, v64, v65
	v_cvt_pk_bf16_f32 v241, v66, v67
	v_cvt_pk_bf16_f32 v242, v68, v69
	v_cvt_pk_bf16_f32 v243, v70, v71
	s_waitcnt vmcnt(6)
	v_lshlrev_b32_e32 v202, 16, v176
	v_and_b32_e32 v203, 0xffff0000, v176
	v_pk_mul_f32 v[72:73], v[72:73], v[202:203]
	v_lshlrev_b32_e32 v194, 16, v177
	v_and_b32_e32 v195, 0xffff0000, v177
	v_pk_mul_f32 v[74:75], v[74:75], v[194:195]
	v_lshlrev_b32_e32 v196, 16, v178
	v_and_b32_e32 v197, 0xffff0000, v178
	v_pk_mul_f32 v[76:77], v[76:77], v[196:197]
	v_lshlrev_b32_e32 v198, 16, v179
	v_and_b32_e32 v199, 0xffff0000, v179
	v_pk_mul_f32 v[78:79], v[78:79], v[198:199]
	v_lshlrev_b32_e32 v200, 16, v244
	v_and_b32_e32 v201, 0xffff0000, v244
	v_pk_add_f32 v[72:73], v[72:73], v[200:201]
	v_lshlrev_b32_e32 v202, 16, v245
	v_and_b32_e32 v203, 0xffff0000, v245
	v_pk_add_f32 v[74:75], v[74:75], v[202:203]
	v_lshlrev_b32_e32 v194, 16, v246
	v_and_b32_e32 v195, 0xffff0000, v246
	v_pk_add_f32 v[76:77], v[76:77], v[194:195]
	v_lshlrev_b32_e32 v196, 16, v247
	v_and_b32_e32 v197, 0xffff0000, v247
	v_pk_add_f32 v[78:79], v[78:79], v[196:197]
	v_cvt_pk_bf16_f32 v244, v72, v73
	v_cvt_pk_bf16_f32 v245, v74, v75
	v_cvt_pk_bf16_f32 v246, v76, v77
	v_cvt_pk_bf16_f32 v247, v78, v79
	s_waitcnt vmcnt(5)
	v_lshlrev_b32_e32 v198, 16, v180
	v_and_b32_e32 v199, 0xffff0000, v180
	v_pk_mul_f32 v[80:81], v[80:81], v[198:199]
	v_lshlrev_b32_e32 v200, 16, v181
	v_and_b32_e32 v201, 0xffff0000, v181
	v_pk_mul_f32 v[82:83], v[82:83], v[200:201]
	v_lshlrev_b32_e32 v202, 16, v182
	v_and_b32_e32 v203, 0xffff0000, v182
	v_pk_mul_f32 v[84:85], v[84:85], v[202:203]
	v_lshlrev_b32_e32 v194, 16, v183
	v_and_b32_e32 v195, 0xffff0000, v183
	v_pk_mul_f32 v[86:87], v[86:87], v[194:195]
	v_lshlrev_b32_e32 v196, 16, v248
	v_and_b32_e32 v197, 0xffff0000, v248
	v_pk_add_f32 v[80:81], v[80:81], v[196:197]
	v_lshlrev_b32_e32 v198, 16, v249
	v_and_b32_e32 v199, 0xffff0000, v249
	v_pk_add_f32 v[82:83], v[82:83], v[198:199]
	v_lshlrev_b32_e32 v200, 16, v250
	v_and_b32_e32 v201, 0xffff0000, v250
	v_pk_add_f32 v[84:85], v[84:85], v[200:201]
	v_lshlrev_b32_e32 v202, 16, v251
	v_and_b32_e32 v203, 0xffff0000, v251
	v_pk_add_f32 v[86:87], v[86:87], v[202:203]
	v_cvt_pk_bf16_f32 v248, v80, v81
	v_cvt_pk_bf16_f32 v249, v82, v83
	v_cvt_pk_bf16_f32 v250, v84, v85
	v_cvt_pk_bf16_f32 v251, v86, v87
	s_waitcnt vmcnt(4)
	v_lshlrev_b32_e32 v194, 16, v0
	v_and_b32_e32 v195, 0xffff0000, v0
	v_pk_mul_f32 v[88:89], v[88:89], v[194:195]
	v_lshlrev_b32_e32 v196, 16, v1
	v_and_b32_e32 v197, 0xffff0000, v1
	v_pk_mul_f32 v[90:91], v[90:91], v[196:197]
	v_lshlrev_b32_e32 v198, 16, v2
	v_and_b32_e32 v199, 0xffff0000, v2
	v_pk_mul_f32 v[92:93], v[92:93], v[198:199]
	v_lshlrev_b32_e32 v200, 16, v3
	v_and_b32_e32 v201, 0xffff0000, v3
	v_pk_mul_f32 v[94:95], v[94:95], v[200:201]
	v_lshlrev_b32_e32 v202, 16, v161
	v_and_b32_e32 v203, 0xffff0000, v161
	v_pk_add_f32 v[88:89], v[88:89], v[202:203]
	v_lshlrev_b32_e32 v194, 16, v163
	v_and_b32_e32 v195, 0xffff0000, v163
	v_pk_add_f32 v[90:91], v[90:91], v[194:195]
	v_lshlrev_b32_e32 v196, 16, v165
	v_and_b32_e32 v197, 0xffff0000, v165
	v_pk_add_f32 v[92:93], v[92:93], v[196:197]
	v_lshlrev_b32_e32 v198, 16, v166
	v_and_b32_e32 v199, 0xffff0000, v166
	v_pk_add_f32 v[94:95], v[94:95], v[198:199]
	v_cvt_pk_bf16_f32 v161, v88, v89
	v_cvt_pk_bf16_f32 v163, v90, v91
	v_cvt_pk_bf16_f32 v165, v92, v93
	v_cvt_pk_bf16_f32 v166, v94, v95
	s_waitcnt vmcnt(3)
	v_lshlrev_b32_e32 v200, 16, v4
	v_and_b32_e32 v201, 0xffff0000, v4
	v_pk_mul_f32 v[96:97], v[96:97], v[200:201]
	v_lshlrev_b32_e32 v202, 16, v5
	v_and_b32_e32 v203, 0xffff0000, v5
	v_pk_mul_f32 v[98:99], v[98:99], v[202:203]
	v_lshlrev_b32_e32 v194, 16, v6
	v_and_b32_e32 v195, 0xffff0000, v6
	v_pk_mul_f32 v[100:101], v[100:101], v[194:195]
	v_lshlrev_b32_e32 v196, 16, v7
	v_and_b32_e32 v197, 0xffff0000, v7
	v_pk_mul_f32 v[102:103], v[102:103], v[196:197]
	v_lshlrev_b32_e32 v198, 16, v167
	v_and_b32_e32 v199, 0xffff0000, v167
	v_pk_add_f32 v[96:97], v[96:97], v[198:199]
	v_lshlrev_b32_e32 v200, 16, v172
	v_and_b32_e32 v201, 0xffff0000, v172
	v_pk_add_f32 v[98:99], v[98:99], v[200:201]
	v_lshlrev_b32_e32 v202, 16, v173
	v_and_b32_e32 v203, 0xffff0000, v173
	v_pk_add_f32 v[100:101], v[100:101], v[202:203]
	v_lshlrev_b32_e32 v194, 16, v234
	v_and_b32_e32 v195, 0xffff0000, v234
	v_pk_add_f32 v[102:103], v[102:103], v[194:195]
	v_cvt_pk_bf16_f32 v167, v96, v97
	v_cvt_pk_bf16_f32 v172, v98, v99
	v_cvt_pk_bf16_f32 v173, v100, v101
	v_cvt_pk_bf16_f32 v234, v102, v103
	s_waitcnt vmcnt(2)
	s_waitcnt lgkmcnt(0)
	v_lshlrev_b32_e32 v196, 16, v128
	v_and_b32_e32 v197, 0xffff0000, v128
	v_pk_mul_f32 v[104:105], v[104:105], v[196:197]
	v_lshlrev_b32_e32 v198, 16, v129
	v_and_b32_e32 v199, 0xffff0000, v129
	v_pk_mul_f32 v[106:107], v[106:107], v[198:199]
	v_lshlrev_b32_e32 v200, 16, v130
	v_and_b32_e32 v201, 0xffff0000, v130
	v_pk_mul_f32 v[108:109], v[108:109], v[200:201]
	v_lshlrev_b32_e32 v202, 16, v131
	v_and_b32_e32 v203, 0xffff0000, v131
	v_pk_mul_f32 v[110:111], v[110:111], v[202:203]
	v_lshlrev_b32_e32 v194, 16, v8
	v_and_b32_e32 v195, 0xffff0000, v8
	v_pk_add_f32 v[104:105], v[104:105], v[194:195]
	v_lshlrev_b32_e32 v196, 16, v9
	v_and_b32_e32 v197, 0xffff0000, v9
	v_pk_add_f32 v[106:107], v[106:107], v[196:197]
	v_lshlrev_b32_e32 v198, 16, v10
	v_and_b32_e32 v199, 0xffff0000, v10
	v_pk_add_f32 v[108:109], v[108:109], v[198:199]
	v_lshlrev_b32_e32 v200, 16, v11
	v_and_b32_e32 v201, 0xffff0000, v11
	v_pk_add_f32 v[110:111], v[110:111], v[200:201]
	v_cvt_pk_bf16_f32 v128, v104, v105
	v_cvt_pk_bf16_f32 v129, v106, v107
	v_cvt_pk_bf16_f32 v130, v108, v109
	v_cvt_pk_bf16_f32 v131, v110, v111
	ds_write_b128 v191, v[128:131] offset:0
	s_waitcnt lgkmcnt(0)
	s_waitcnt vmcnt(1)
	s_waitcnt lgkmcnt(0)
	v_lshlrev_b32_e32 v202, 16, v12
	v_and_b32_e32 v203, 0xffff0000, v12
	v_pk_mul_f32 v[112:113], v[112:113], v[202:203]
	v_lshlrev_b32_e32 v194, 16, v13
	v_and_b32_e32 v195, 0xffff0000, v13
	v_pk_mul_f32 v[114:115], v[114:115], v[194:195]
	v_lshlrev_b32_e32 v196, 16, v14
	v_and_b32_e32 v197, 0xffff0000, v14
	v_pk_mul_f32 v[116:117], v[116:117], v[196:197]
	v_lshlrev_b32_e32 v198, 16, v15
	v_and_b32_e32 v199, 0xffff0000, v15
	v_pk_mul_f32 v[118:119], v[118:119], v[198:199]
	v_lshlrev_b32_e32 v200, 16, v16
	v_and_b32_e32 v201, 0xffff0000, v16
	v_pk_add_f32 v[112:113], v[112:113], v[200:201]
	v_lshlrev_b32_e32 v202, 16, v17
	v_and_b32_e32 v203, 0xffff0000, v17
	v_pk_add_f32 v[114:115], v[114:115], v[202:203]
	v_lshlrev_b32_e32 v194, 16, v18
	v_and_b32_e32 v195, 0xffff0000, v18
	v_pk_add_f32 v[116:117], v[116:117], v[194:195]
	v_lshlrev_b32_e32 v196, 16, v19
	v_and_b32_e32 v197, 0xffff0000, v19
	v_pk_add_f32 v[118:119], v[118:119], v[196:197]
	v_cvt_pk_bf16_f32 v12, v112, v113
	v_cvt_pk_bf16_f32 v13, v114, v115
	v_cvt_pk_bf16_f32 v14, v116, v117
	v_cvt_pk_bf16_f32 v15, v118, v119
	ds_write_b128 v191, v[12:15] offset:8192
	s_waitcnt lgkmcnt(0)
	s_waitcnt vmcnt(0)
	s_waitcnt lgkmcnt(0)
	v_lshlrev_b32_e32 v198, 16, v132
	v_and_b32_e32 v199, 0xffff0000, v132
	v_pk_mul_f32 v[120:121], v[120:121], v[198:199]
	v_lshlrev_b32_e32 v200, 16, v133
	v_and_b32_e32 v201, 0xffff0000, v133
	v_pk_mul_f32 v[122:123], v[122:123], v[200:201]
	v_lshlrev_b32_e32 v202, 16, v134
	v_and_b32_e32 v203, 0xffff0000, v134
	v_pk_mul_f32 v[124:125], v[124:125], v[202:203]
	v_lshlrev_b32_e32 v194, 16, v135
	v_and_b32_e32 v195, 0xffff0000, v135
	v_pk_mul_f32 v[126:127], v[126:127], v[194:195]
	v_lshlrev_b32_e32 v196, 16, v20
	v_and_b32_e32 v197, 0xffff0000, v20
	v_pk_add_f32 v[120:121], v[120:121], v[196:197]
	v_lshlrev_b32_e32 v198, 16, v21
	v_and_b32_e32 v199, 0xffff0000, v21
	v_pk_add_f32 v[122:123], v[122:123], v[198:199]
	v_lshlrev_b32_e32 v200, 16, v22
	v_and_b32_e32 v201, 0xffff0000, v22
	v_pk_add_f32 v[124:125], v[124:125], v[200:201]
	v_lshlrev_b32_e32 v202, 16, v23
	v_and_b32_e32 v203, 0xffff0000, v23
	v_pk_add_f32 v[126:127], v[126:127], v[202:203]
	v_cvt_pk_bf16_f32 v132, v120, v121
	v_cvt_pk_bf16_f32 v133, v122, v123
	v_cvt_pk_bf16_f32 v134, v124, v125
	v_cvt_pk_bf16_f32 v135, v126, v127
	ds_write_b128 v191, v[132:135] offset:16384
	s_waitcnt lgkmcnt(0)
	s_branch .Lmepi_done
.Lmepi_z3:
	global_load_dwordx4 v[128:131], v[192:193], off nt
	global_load_dwordx4 v[132:135], v[192:193], off offset:256 nt
	s_mov_b32 s58, 0x20000
	v_lshl_add_u64 v[194:195], v[192:193], 0, s[58:59]
	global_load_dwordx4 v[136:139], v[194:195], off nt
	global_load_dwordx4 v[140:143], v[194:195], off offset:256 nt
	s_mov_b32 s58, 0x40000
	v_lshl_add_u64 v[196:197], v[192:193], 0, s[58:59]
	global_load_dwordx4 v[144:147], v[196:197], off nt
	global_load_dwordx4 v[148:151], v[196:197], off offset:256 nt
	s_mov_b32 s58, 0x60000
	v_lshl_add_u64 v[198:199], v[192:193], 0, s[58:59]
	global_load_dwordx4 v[152:155], v[198:199], off nt
	global_load_dwordx4 v[156:159], v[198:199], off offset:256 nt
	s_mov_b32 s58, 0x100000
	v_lshl_add_u64 v[200:201], v[192:193], 0, s[58:59]
	global_load_dwordx4 v[168:171], v[200:201], off nt
	global_load_dwordx4 v[176:179], v[200:201], off offset:256 nt
	s_waitcnt vmcnt(9)
	v_lshlrev_b32_e32 v202, 16, v128
	v_and_b32_e32 v203, 0xffff0000, v128
	v_pk_mul_f32 v[0:1], v[0:1], v[202:203]
	v_lshlrev_b32_e32 v194, 16, v129
	v_and_b32_e32 v195, 0xffff0000, v129
	v_pk_mul_f32 v[2:3], v[2:3], v[194:195]
	v_lshlrev_b32_e32 v196, 16, v130
	v_and_b32_e32 v197, 0xffff0000, v130
	v_pk_mul_f32 v[4:5], v[4:5], v[196:197]
	v_lshlrev_b32_e32 v198, 16, v131
	v_and_b32_e32 v199, 0xffff0000, v131
	v_pk_mul_f32 v[6:7], v[6:7], v[198:199]
	v_lshlrev_b32_e32 v200, 16, v204
	v_and_b32_e32 v201, 0xffff0000, v204
	v_pk_add_f32 v[0:1], v[0:1], v[200:201]
	v_lshlrev_b32_e32 v202, 16, v205
	v_and_b32_e32 v203, 0xffff0000, v205
	v_pk_add_f32 v[2:3], v[2:3], v[202:203]
	v_lshlrev_b32_e32 v194, 16, v206
	v_and_b32_e32 v195, 0xffff0000, v206
	v_pk_add_f32 v[4:5], v[4:5], v[194:195]
	v_lshlrev_b32_e32 v196, 16, v207
	v_and_b32_e32 v197, 0xffff0000, v207
	v_pk_add_f32 v[6:7], v[6:7], v[196:197]
	v_cvt_pk_bf16_f32 v128, v0, v1
	v_cvt_pk_bf16_f32 v129, v2, v3
	v_cvt_pk_bf16_f32 v130, v4, v5
	v_cvt_pk_bf16_f32 v131, v6, v7
	global_store_dwordx4 v[188:189], v[128:131], off sc1
	s_waitcnt vmcnt(9)
	v_lshlrev_b32_e32 v198, 16, v132
	v_and_b32_e32 v199, 0xffff0000, v132
	v_pk_mul_f32 v[8:9], v[8:9], v[198:199]
	v_lshlrev_b32_e32 v200, 16, v133
	v_and_b32_e32 v201, 0xffff0000, v133
	v_pk_mul_f32 v[10:11], v[10:11], v[200:201]
	v_lshlrev_b32_e32 v202, 16, v134
	v_and_b32_e32 v203, 0xffff0000, v134
	v_pk_mul_f32 v[12:13], v[12:13], v[202:203]
	v_lshlrev_b32_e32 v194, 16, v135
	v_and_b32_e32 v195, 0xffff0000, v135
	v_pk_mul_f32 v[14:15], v[14:15], v[194:195]
	v_lshlrev_b32_e32 v196, 16, v208
	v_and_b32_e32 v197, 0xffff0000, v208
	v_pk_add_f32 v[8:9], v[8:9], v[196:197]
	v_lshlrev_b32_e32 v198, 16, v209
	v_and_b32_e32 v199, 0xffff0000, v209
	v_pk_add_f32 v[10:11], v[10:11], v[198:199]
	v_lshlrev_b32_e32 v200, 16, v210
	v_and_b32_e32 v201, 0xffff0000, v210
	v_pk_add_f32 v[12:13], v[12:13], v[200:201]
	v_lshlrev_b32_e32 v202, 16, v211
	v_and_b32_e32 v203, 0xffff0000, v211
	v_pk_add_f32 v[14:15], v[14:15], v[202:203]
	v_cvt_pk_bf16_f32 v132, v8, v9
	v_cvt_pk_bf16_f32 v133, v10, v11
	v_cvt_pk_bf16_f32 v134, v12, v13
	v_cvt_pk_bf16_f32 v135, v14, v15
	global_store_dwordx4 v[188:189], v[132:135], off offset:256 sc1
	s_mov_b32 s58, 0x120000
	v_lshl_add_u64 v[194:195], v[192:193], 0, s[58:59]
	global_load_dwordx4 v[180:183], v[194:195], off nt
	global_load_dwordx4 v[0:3], v[194:195], off offset:256 nt
	s_mov_b32 s58, 0x140000
	v_lshl_add_u64 v[196:197], v[192:193], 0, s[58:59]
	global_load_dwordx4 v[4:7], v[196:197], off nt
	global_load_dwordx4 v[128:131], v[196:197], off offset:256 nt
	ds_read_b128 v[8:11], v191 offset:0
	s_waitcnt vmcnt(13)
	v_lshlrev_b32_e32 v198, 16, v136
	v_and_b32_e32 v199, 0xffff0000, v136
	v_pk_mul_f32 v[16:17], v[16:17], v[198:199]
	v_lshlrev_b32_e32 v200, 16, v137
	v_and_b32_e32 v201, 0xffff0000, v137
	v_pk_mul_f32 v[18:19], v[18:19], v[200:201]
	v_lshlrev_b32_e32 v202, 16, v138
	v_and_b32_e32 v203, 0xffff0000, v138
	v_pk_mul_f32 v[20:21], v[20:21], v[202:203]
	v_lshlrev_b32_e32 v194, 16, v139
	v_and_b32_e32 v195, 0xffff0000, v139
	v_pk_mul_f32 v[22:23], v[22:23], v[194:195]
	v_lshlrev_b32_e32 v196, 16, v212
	v_and_b32_e32 v197, 0xffff0000, v212
	v_pk_add_f32 v[16:17], v[16:17], v[196:197]
	v_lshlrev_b32_e32 v198, 16, v213
	v_and_b32_e32 v199, 0xffff0000, v213
	v_pk_add_f32 v[18:19], v[18:19], v[198:199]
	v_lshlrev_b32_e32 v200, 16, v214
	v_and_b32_e32 v201, 0xffff0000, v214
	v_pk_add_f32 v[20:21], v[20:21], v[200:201]
	v_lshlrev_b32_e32 v202, 16, v215
	v_and_b32_e32 v203, 0xffff0000, v215
	v_pk_add_f32 v[22:23], v[22:23], v[202:203]
	v_cvt_pk_bf16_f32 v136, v16, v17
	v_cvt_pk_bf16_f32 v137, v18, v19
	v_cvt_pk_bf16_f32 v138, v20, v21
	v_cvt_pk_bf16_f32 v139, v22, v23
	s_mov_b32 s58, 0x8000
	v_lshl_add_u64 v[194:195], v[188:189], 0, s[58:59]
	global_store_dwordx4 v[194:195], v[136:139], off sc1
	s_waitcnt vmcnt(13)
	v_lshlrev_b32_e32 v196, 16, v140
	v_and_b32_e32 v197, 0xffff0000, v140
	v_pk_mul_f32 v[24:25], v[24:25], v[196:197]
	v_lshlrev_b32_e32 v198, 16, v141
	v_and_b32_e32 v199, 0xffff0000, v141
	v_pk_mul_f32 v[26:27], v[26:27], v[198:199]
	v_lshlrev_b32_e32 v200, 16, v142
	v_and_b32_e32 v201, 0xffff0000, v142
	v_pk_mul_f32 v[28:29], v[28:29], v[200:201]
	v_lshlrev_b32_e32 v202, 16, v143
	v_and_b32_e32 v203, 0xffff0000, v143
	v_pk_mul_f32 v[30:31], v[30:31], v[202:203]
	v_lshlrev_b32_e32 v194, 16, v216
	v_and_b32_e32 v195, 0xffff0000, v216
	v_pk_add_f32 v[24:25], v[24:25], v[194:195]
	v_lshlrev_b32_e32 v196, 16, v217
	v_and_b32_e32 v197, 0xffff0000, v217
	v_pk_add_f32 v[26:27], v[26:27], v[196:197]
	v_lshlrev_b32_e32 v198, 16, v218
	v_and_b32_e32 v199, 0xffff0000, v218
	v_pk_add_f32 v[28:29], v[28:29], v[198:199]
	v_lshlrev_b32_e32 v200, 16, v219
	v_and_b32_e32 v201, 0xffff0000, v219
	v_pk_add_f32 v[30:31], v[30:31], v[200:201]
	v_cvt_pk_bf16_f32 v140, v24, v25
	v_cvt_pk_bf16_f32 v141, v26, v27
	v_cvt_pk_bf16_f32 v142, v28, v29
	v_cvt_pk_bf16_f32 v143, v30, v31
	s_mov_b32 s58, 0x8000
	v_lshl_add_u64 v[202:203], v[188:189], 0, s[58:59]
	global_store_dwordx4 v[202:203], v[140:143], off offset:256 sc1
	s_mov_b32 s58, 0x160000
	v_lshl_add_u64 v[194:195], v[192:193], 0, s[58:59]
	global_load_dwordx4 v[12:15], v[194:195], off nt
	global_load_dwordx4 v[132:135], v[194:195], off offset:256 nt
	ds_read_b128 v[16:19], v191 offset:8192
	ds_read_b128 v[20:23], v191 offset:16384
	s_waitcnt vmcnt(15)
	v_lshlrev_b32_e32 v196, 16, v144
	v_and_b32_e32 v197, 0xffff0000, v144
	v_pk_mul_f32 v[32:33], v[32:33], v[196:197]
	v_lshlrev_b32_e32 v198, 16, v145
	v_and_b32_e32 v199, 0xffff0000, v145
	v_pk_mul_f32 v[34:35], v[34:35], v[198:199]
	v_lshlrev_b32_e32 v200, 16, v146
	v_and_b32_e32 v201, 0xffff0000, v146
	v_pk_mul_f32 v[36:37], v[36:37], v[200:201]
	v_lshlrev_b32_e32 v202, 16, v147
	v_and_b32_e32 v203, 0xffff0000, v147
	v_pk_mul_f32 v[38:39], v[38:39], v[202:203]
	v_lshlrev_b32_e32 v194, 16, v220
	v_and_b32_e32 v195, 0xffff0000, v220
	v_pk_add_f32 v[32:33], v[32:33], v[194:195]
	v_lshlrev_b32_e32 v196, 16, v221
	v_and_b32_e32 v197, 0xffff0000, v221
	v_pk_add_f32 v[34:35], v[34:35], v[196:197]
	v_lshlrev_b32_e32 v198, 16, v222
	v_and_b32_e32 v199, 0xffff0000, v222
	v_pk_add_f32 v[36:37], v[36:37], v[198:199]
	v_lshlrev_b32_e32 v200, 16, v223
	v_and_b32_e32 v201, 0xffff0000, v223
	v_pk_add_f32 v[38:39], v[38:39], v[200:201]
	v_cvt_pk_bf16_f32 v144, v32, v33
	v_cvt_pk_bf16_f32 v145, v34, v35
	v_cvt_pk_bf16_f32 v146, v36, v37
	v_cvt_pk_bf16_f32 v147, v38, v39
	s_mov_b32 s58, 0x10000
	v_lshl_add_u64 v[202:203], v[188:189], 0, s[58:59]
	global_store_dwordx4 v[202:203], v[144:147], off sc1
	s_waitcnt vmcnt(15)
	v_lshlrev_b32_e32 v194, 16, v148
	v_and_b32_e32 v195, 0xffff0000, v148
	v_pk_mul_f32 v[40:41], v[40:41], v[194:195]
	v_lshlrev_b32_e32 v196, 16, v149
	v_and_b32_e32 v197, 0xffff0000, v149
	v_pk_mul_f32 v[42:43], v[42:43], v[196:197]
	v_lshlrev_b32_e32 v198, 16, v150
	v_and_b32_e32 v199, 0xffff0000, v150
	v_pk_mul_f32 v[44:45], v[44:45], v[198:199]
	v_lshlrev_b32_e32 v200, 16, v151
	v_and_b32_e32 v201, 0xffff0000, v151
	v_pk_mul_f32 v[46:47], v[46:47], v[200:201]
	v_lshlrev_b32_e32 v202, 16, v224
	v_and_b32_e32 v203, 0xffff0000, v224
	v_pk_add_f32 v[40:41], v[40:41], v[202:203]
	v_lshlrev_b32_e32 v194, 16, v225
	v_and_b32_e32 v195, 0xffff0000, v225
	v_pk_add_f32 v[42:43], v[42:43], v[194:195]
	v_lshlrev_b32_e32 v196, 16, v226
	v_and_b32_e32 v197, 0xffff0000, v226
	v_pk_add_f32 v[44:45], v[44:45], v[196:197]
	v_lshlrev_b32_e32 v198, 16, v227
	v_and_b32_e32 v199, 0xffff0000, v227
	v_pk_add_f32 v[46:47], v[46:47], v[198:199]
	v_cvt_pk_bf16_f32 v148, v40, v41
	v_cvt_pk_bf16_f32 v149, v42, v43
	v_cvt_pk_bf16_f32 v150, v44, v45
	v_cvt_pk_bf16_f32 v151, v46, v47
	s_mov_b32 s58, 0x10000
	v_lshl_add_u64 v[200:201], v[188:189], 0, s[58:59]
	global_store_dwordx4 v[200:201], v[148:151], off offset:256 sc1
	s_waitcnt vmcnt(15)
	v_lshlrev_b32_e32 v202, 16, v152
	v_and_b32_e32 v203, 0xffff0000, v152
	v_pk_mul_f32 v[48:49], v[48:49], v[202:203]
	v_lshlrev_b32_e32 v194, 16, v153
	v_and_b32_e32 v195, 0xffff0000, v153
	v_pk_mul_f32 v[50:51], v[50:51], v[194:195]
	v_lshlrev_b32_e32 v196, 16, v154
	v_and_b32_e32 v197, 0xffff0000, v154
	v_pk_mul_f32 v[52:53], v[52:53], v[196:197]
	v_lshlrev_b32_e32 v198, 16, v155
	v_and_b32_e32 v199, 0xffff0000, v155
	v_pk_mul_f32 v[54:55], v[54:55], v[198:199]
	v_lshlrev_b32_e32 v200, 16, v228
	v_and_b32_e32 v201, 0xffff0000, v228
	v_pk_add_f32 v[48:49], v[48:49], v[200:201]
	v_lshlrev_b32_e32 v202, 16, v229
	v_and_b32_e32 v203, 0xffff0000, v229
	v_pk_add_f32 v[50:51], v[50:51], v[202:203]
	v_lshlrev_b32_e32 v194, 16, v230
	v_and_b32_e32 v195, 0xffff0000, v230
	v_pk_add_f32 v[52:53], v[52:53], v[194:195]
	v_lshlrev_b32_e32 v196, 16, v231
	v_and_b32_e32 v197, 0xffff0000, v231
	v_pk_add_f32 v[54:55], v[54:55], v[196:197]
	v_cvt_pk_bf16_f32 v152, v48, v49
	v_cvt_pk_bf16_f32 v153, v50, v51
	v_cvt_pk_bf16_f32 v154, v52, v53
	v_cvt_pk_bf16_f32 v155, v54, v55
	s_mov_b32 s58, 0x18000
	v_lshl_add_u64 v[198:199], v[188:189], 0, s[58:59]
	global_store_dwordx4 v[198:199], v[152:155], off sc1
	s_waitcnt vmcnt(15)
	v_lshlrev_b32_e32 v200, 16, v156
	v_and_b32_e32 v201, 0xffff0000, v156
	v_pk_mul_f32 v[56:57], v[56:57], v[200:201]
	v_lshlrev_b32_e32 v202, 16, v157
	v_and_b32_e32 v203, 0xffff0000, v157
	v_pk_mul_f32 v[58:59], v[58:59], v[202:203]
	v_lshlrev_b32_e32 v194, 16, v158
	v_and_b32_e32 v195, 0xffff0000, v158
	v_pk_mul_f32 v[60:61], v[60:61], v[194:195]
	v_lshlrev_b32_e32 v196, 16, v159
	v_and_b32_e32 v197, 0xffff0000, v159
	v_pk_mul_f32 v[62:63], v[62:63], v[196:197]
	v_lshlrev_b32_e32 v198, 16, v236
	v_and_b32_e32 v199, 0xffff0000, v236
	v_pk_add_f32 v[56:57], v[56:57], v[198:199]
	v_lshlrev_b32_e32 v200, 16, v237
	v_and_b32_e32 v201, 0xffff0000, v237
	v_pk_add_f32 v[58:59], v[58:59], v[200:201]
	v_lshlrev_b32_e32 v202, 16, v238
	v_and_b32_e32 v203, 0xffff0000, v238
	v_pk_add_f32 v[60:61], v[60:61], v[202:203]
	v_lshlrev_b32_e32 v194, 16, v239
	v_and_b32_e32 v195, 0xffff0000, v239
	v_pk_add_f32 v[62:63], v[62:63], v[194:195]
	v_cvt_pk_bf16_f32 v156, v56, v57
	v_cvt_pk_bf16_f32 v157, v58, v59
	v_cvt_pk_bf16_f32 v158, v60, v61
	v_cvt_pk_bf16_f32 v159, v62, v63
	s_mov_b32 s58, 0x18000
	v_lshl_add_u64 v[196:197], v[188:189], 0, s[58:59]
	global_store_dwordx4 v[196:197], v[156:159], off offset:256 sc1
	s_waitcnt vmcnt(15)
	v_lshlrev_b32_e32 v198, 16, v168
	v_and_b32_e32 v199, 0xffff0000, v168
	v_pk_mul_f32 v[64:65], v[64:65], v[198:199]
	v_lshlrev_b32_e32 v200, 16, v169
	v_and_b32_e32 v201, 0xffff0000, v169
	v_pk_mul_f32 v[66:67], v[66:67], v[200:201]
	v_lshlrev_b32_e32 v202, 16, v170
	v_and_b32_e32 v203, 0xffff0000, v170
	v_pk_mul_f32 v[68:69], v[68:69], v[202:203]
	v_lshlrev_b32_e32 v194, 16, v171
	v_and_b32_e32 v195, 0xffff0000, v171
	v_pk_mul_f32 v[70:71], v[70:71], v[194:195]
	v_lshlrev_b32_e32 v196, 16, v240
	v_and_b32_e32 v197, 0xffff0000, v240
	v_pk_add_f32 v[64:65], v[64:65], v[196:197]
	v_lshlrev_b32_e32 v198, 16, v241
	v_and_b32_e32 v199, 0xffff0000, v241
	v_pk_add_f32 v[66:67], v[66:67], v[198:199]
	v_lshlrev_b32_e32 v200, 16, v242
	v_and_b32_e32 v201, 0xffff0000, v242
	v_pk_add_f32 v[68:69], v[68:69], v[200:201]
	v_lshlrev_b32_e32 v202, 16, v243
	v_and_b32_e32 v203, 0xffff0000, v243
	v_pk_add_f32 v[70:71], v[70:71], v[202:203]
	v_cvt_pk_bf16_f32 v168, v64, v65
	v_cvt_pk_bf16_f32 v169, v66, v67
	v_cvt_pk_bf16_f32 v170, v68, v69
	v_cvt_pk_bf16_f32 v171, v70, v71
	s_mov_b32 s58, 0x40000
	v_lshl_add_u64 v[194:195], v[188:189], 0, s[58:59]
	global_store_dwordx4 v[194:195], v[168:171], off sc1
	s_waitcnt vmcnt(15)
	v_lshlrev_b32_e32 v196, 16, v176
	v_and_b32_e32 v197, 0xffff0000, v176
	v_pk_mul_f32 v[72:73], v[72:73], v[196:197]
	v_lshlrev_b32_e32 v198, 16, v177
	v_and_b32_e32 v199, 0xffff0000, v177
	v_pk_mul_f32 v[74:75], v[74:75], v[198:199]
	v_lshlrev_b32_e32 v200, 16, v178
	v_and_b32_e32 v201, 0xffff0000, v178
	v_pk_mul_f32 v[76:77], v[76:77], v[200:201]
	v_lshlrev_b32_e32 v202, 16, v179
	v_and_b32_e32 v203, 0xffff0000, v179
	v_pk_mul_f32 v[78:79], v[78:79], v[202:203]
	v_lshlrev_b32_e32 v194, 16, v244
	v_and_b32_e32 v195, 0xffff0000, v244
	v_pk_add_f32 v[72:73], v[72:73], v[194:195]
	v_lshlrev_b32_e32 v196, 16, v245
	v_and_b32_e32 v197, 0xffff0000, v245
	v_pk_add_f32 v[74:75], v[74:75], v[196:197]
	v_lshlrev_b32_e32 v198, 16, v246
	v_and_b32_e32 v199, 0xffff0000, v246
	v_pk_add_f32 v[76:77], v[76:77], v[198:199]
	v_lshlrev_b32_e32 v200, 16, v247
	v_and_b32_e32 v201, 0xffff0000, v247
	v_pk_add_f32 v[78:79], v[78:79], v[200:201]
	v_cvt_pk_bf16_f32 v176, v72, v73
	v_cvt_pk_bf16_f32 v177, v74, v75
	v_cvt_pk_bf16_f32 v178, v76, v77
	v_cvt_pk_bf16_f32 v179, v78, v79
	s_mov_b32 s58, 0x40000
	v_lshl_add_u64 v[202:203], v[188:189], 0, s[58:59]
	global_store_dwordx4 v[202:203], v[176:179], off offset:256 sc1
	s_waitcnt vmcnt(13)
	v_lshlrev_b32_e32 v194, 16, v180
	v_and_b32_e32 v195, 0xffff0000, v180
	v_pk_mul_f32 v[80:81], v[80:81], v[194:195]
	v_lshlrev_b32_e32 v196, 16, v181
	v_and_b32_e32 v197, 0xffff0000, v181
	v_pk_mul_f32 v[82:83], v[82:83], v[196:197]
	v_lshlrev_b32_e32 v198, 16, v182
	v_and_b32_e32 v199, 0xffff0000, v182
	v_pk_mul_f32 v[84:85], v[84:85], v[198:199]
	v_lshlrev_b32_e32 v200, 16, v183
	v_and_b32_e32 v201, 0xffff0000, v183
	v_pk_mul_f32 v[86:87], v[86:87], v[200:201]
	v_lshlrev_b32_e32 v202, 16, v248
	v_and_b32_e32 v203, 0xffff0000, v248
	v_pk_add_f32 v[80:81], v[80:81], v[202:203]
	v_lshlrev_b32_e32 v194, 16, v249
	v_and_b32_e32 v195, 0xffff0000, v249
	v_pk_add_f32 v[82:83], v[82:83], v[194:195]
	v_lshlrev_b32_e32 v196, 16, v250
	v_and_b32_e32 v197, 0xffff0000, v250
	v_pk_add_f32 v[84:85], v[84:85], v[196:197]
	v_lshlrev_b32_e32 v198, 16, v251
	v_and_b32_e32 v199, 0xffff0000, v251
	v_pk_add_f32 v[86:87], v[86:87], v[198:199]
	v_cvt_pk_bf16_f32 v180, v80, v81
	v_cvt_pk_bf16_f32 v181, v82, v83
	v_cvt_pk_bf16_f32 v182, v84, v85
	v_cvt_pk_bf16_f32 v183, v86, v87
	s_mov_b32 s58, 0x48000
	v_lshl_add_u64 v[200:201], v[188:189], 0, s[58:59]
	global_store_dwordx4 v[200:201], v[180:183], off sc1
	s_waitcnt vmcnt(13)
	v_lshlrev_b32_e32 v202, 16, v0
	v_and_b32_e32 v203, 0xffff0000, v0
	v_pk_mul_f32 v[88:89], v[88:89], v[202:203]
	v_lshlrev_b32_e32 v194, 16, v1
	v_and_b32_e32 v195, 0xffff0000, v1
	v_pk_mul_f32 v[90:91], v[90:91], v[194:195]
	v_lshlrev_b32_e32 v196, 16, v2
	v_and_b32_e32 v197, 0xffff0000, v2
	v_pk_mul_f32 v[92:93], v[92:93], v[196:197]
	v_lshlrev_b32_e32 v198, 16, v3
	v_and_b32_e32 v199, 0xffff0000, v3
	v_pk_mul_f32 v[94:95], v[94:95], v[198:199]
	v_lshlrev_b32_e32 v200, 16, v161
	v_and_b32_e32 v201, 0xffff0000, v161
	v_pk_add_f32 v[88:89], v[88:89], v[200:201]
	v_lshlrev_b32_e32 v202, 16, v163
	v_and_b32_e32 v203, 0xffff0000, v163
	v_pk_add_f32 v[90:91], v[90:91], v[202:203]
	v_lshlrev_b32_e32 v194, 16, v165
	v_and_b32_e32 v195, 0xffff0000, v165
	v_pk_add_f32 v[92:93], v[92:93], v[194:195]
	v_lshlrev_b32_e32 v196, 16, v166
	v_and_b32_e32 v197, 0xffff0000, v166
	v_pk_add_f32 v[94:95], v[94:95], v[196:197]
	v_cvt_pk_bf16_f32 v0, v88, v89
	v_cvt_pk_bf16_f32 v1, v90, v91
	v_cvt_pk_bf16_f32 v2, v92, v93
	v_cvt_pk_bf16_f32 v3, v94, v95
	s_mov_b32 s58, 0x48000
	v_lshl_add_u64 v[198:199], v[188:189], 0, s[58:59]
	global_store_dwordx4 v[198:199], v[0:3], off offset:256 sc1
	s_waitcnt vmcnt(13)
	v_lshlrev_b32_e32 v200, 16, v4
	v_and_b32_e32 v201, 0xffff0000, v4
	v_pk_mul_f32 v[96:97], v[96:97], v[200:201]
	v_lshlrev_b32_e32 v202, 16, v5
	v_and_b32_e32 v203, 0xffff0000, v5
	v_pk_mul_f32 v[98:99], v[98:99], v[202:203]
	v_lshlrev_b32_e32 v194, 16, v6
	v_and_b32_e32 v195, 0xffff0000, v6
	v_pk_mul_f32 v[100:101], v[100:101], v[194:195]
	v_lshlrev_b32_e32 v196, 16, v7
	v_and_b32_e32 v197, 0xffff0000, v7
	v_pk_mul_f32 v[102:103], v[102:103], v[196:197]
	v_lshlrev_b32_e32 v198, 16, v167
	v_and_b32_e32 v199, 0xffff0000, v167
	v_pk_add_f32 v[96:97], v[96:97], v[198:199]
	v_lshlrev_b32_e32 v200, 16, v172
	v_and_b32_e32 v201, 0xffff0000, v172
	v_pk_add_f32 v[98:99], v[98:99], v[200:201]
	v_lshlrev_b32_e32 v202, 16, v173
	v_and_b32_e32 v203, 0xffff0000, v173
	v_pk_add_f32 v[100:101], v[100:101], v[202:203]
	v_lshlrev_b32_e32 v194, 16, v234
	v_and_b32_e32 v195, 0xffff0000, v234
	v_pk_add_f32 v[102:103], v[102:103], v[194:195]
	v_cvt_pk_bf16_f32 v4, v96, v97
	v_cvt_pk_bf16_f32 v5, v98, v99
	v_cvt_pk_bf16_f32 v6, v100, v101
	v_cvt_pk_bf16_f32 v7, v102, v103
	s_mov_b32 s58, 0x50000
	v_lshl_add_u64 v[196:197], v[188:189], 0, s[58:59]
	global_store_dwordx4 v[196:197], v[4:7], off sc1
	s_waitcnt vmcnt(13)
	s_waitcnt lgkmcnt(0)
	v_lshlrev_b32_e32 v198, 16, v128
	v_and_b32_e32 v199, 0xffff0000, v128
	v_pk_mul_f32 v[104:105], v[104:105], v[198:199]
	v_lshlrev_b32_e32 v200, 16, v129
	v_and_b32_e32 v201, 0xffff0000, v129
	v_pk_mul_f32 v[106:107], v[106:107], v[200:201]
	v_lshlrev_b32_e32 v202, 16, v130
	v_and_b32_e32 v203, 0xffff0000, v130
	v_pk_mul_f32 v[108:109], v[108:109], v[202:203]
	v_lshlrev_b32_e32 v194, 16, v131
	v_and_b32_e32 v195, 0xffff0000, v131
	v_pk_mul_f32 v[110:111], v[110:111], v[194:195]
	v_lshlrev_b32_e32 v196, 16, v8
	v_and_b32_e32 v197, 0xffff0000, v8
	v_pk_add_f32 v[104:105], v[104:105], v[196:197]
	v_lshlrev_b32_e32 v198, 16, v9
	v_and_b32_e32 v199, 0xffff0000, v9
	v_pk_add_f32 v[106:107], v[106:107], v[198:199]
	v_lshlrev_b32_e32 v200, 16, v10
	v_and_b32_e32 v201, 0xffff0000, v10
	v_pk_add_f32 v[108:109], v[108:109], v[200:201]
	v_lshlrev_b32_e32 v202, 16, v11
	v_and_b32_e32 v203, 0xffff0000, v11
	v_pk_add_f32 v[110:111], v[110:111], v[202:203]
	v_cvt_pk_bf16_f32 v128, v104, v105
	v_cvt_pk_bf16_f32 v129, v106, v107
	v_cvt_pk_bf16_f32 v130, v108, v109
	v_cvt_pk_bf16_f32 v131, v110, v111
	s_mov_b32 s58, 0x50000
	v_lshl_add_u64 v[194:195], v[188:189], 0, s[58:59]
	global_store_dwordx4 v[194:195], v[128:131], off offset:256 sc1
	s_waitcnt vmcnt(11)
	s_waitcnt lgkmcnt(0)
	v_lshlrev_b32_e32 v196, 16, v12
	v_and_b32_e32 v197, 0xffff0000, v12
	v_pk_mul_f32 v[112:113], v[112:113], v[196:197]
	v_lshlrev_b32_e32 v198, 16, v13
	v_and_b32_e32 v199, 0xffff0000, v13
	v_pk_mul_f32 v[114:115], v[114:115], v[198:199]
	v_lshlrev_b32_e32 v200, 16, v14
	v_and_b32_e32 v201, 0xffff0000, v14
	v_pk_mul_f32 v[116:117], v[116:117], v[200:201]
	v_lshlrev_b32_e32 v202, 16, v15
	v_and_b32_e32 v203, 0xffff0000, v15
	v_pk_mul_f32 v[118:119], v[118:119], v[202:203]
	v_lshlrev_b32_e32 v194, 16, v16
	v_and_b32_e32 v195, 0xffff0000, v16
	v_pk_add_f32 v[112:113], v[112:113], v[194:195]
	v_lshlrev_b32_e32 v196, 16, v17
	v_and_b32_e32 v197, 0xffff0000, v17
	v_pk_add_f32 v[114:115], v[114:115], v[196:197]
	v_lshlrev_b32_e32 v198, 16, v18
	v_and_b32_e32 v199, 0xffff0000, v18
	v_pk_add_f32 v[116:117], v[116:117], v[198:199]
	v_lshlrev_b32_e32 v200, 16, v19
	v_and_b32_e32 v201, 0xffff0000, v19
	v_pk_add_f32 v[118:119], v[118:119], v[200:201]
	v_cvt_pk_bf16_f32 v12, v112, v113
	v_cvt_pk_bf16_f32 v13, v114, v115
	v_cvt_pk_bf16_f32 v14, v116, v117
	v_cvt_pk_bf16_f32 v15, v118, v119
	s_mov_b32 s58, 0x58000
	v_lshl_add_u64 v[202:203], v[188:189], 0, s[58:59]
	global_store_dwordx4 v[202:203], v[12:15], off sc1
	s_waitcnt vmcnt(11)
	s_waitcnt lgkmcnt(0)
	v_lshlrev_b32_e32 v194, 16, v132
	v_and_b32_e32 v195, 0xffff0000, v132
	v_pk_mul_f32 v[120:121], v[120:121], v[194:195]
	v_lshlrev_b32_e32 v196, 16, v133
	v_and_b32_e32 v197, 0xffff0000, v133
	v_pk_mul_f32 v[122:123], v[122:123], v[196:197]
	v_lshlrev_b32_e32 v198, 16, v134
	v_and_b32_e32 v199, 0xffff0000, v134
	v_pk_mul_f32 v[124:125], v[124:125], v[198:199]
	v_lshlrev_b32_e32 v200, 16, v135
	v_and_b32_e32 v201, 0xffff0000, v135
	v_pk_mul_f32 v[126:127], v[126:127], v[200:201]
	v_lshlrev_b32_e32 v202, 16, v20
	v_and_b32_e32 v203, 0xffff0000, v20
	v_pk_add_f32 v[120:121], v[120:121], v[202:203]
	v_lshlrev_b32_e32 v194, 16, v21
	v_and_b32_e32 v195, 0xffff0000, v21
	v_pk_add_f32 v[122:123], v[122:123], v[194:195]
	v_lshlrev_b32_e32 v196, 16, v22
	v_and_b32_e32 v197, 0xffff0000, v22
	v_pk_add_f32 v[124:125], v[124:125], v[196:197]
	v_lshlrev_b32_e32 v198, 16, v23
	v_and_b32_e32 v199, 0xffff0000, v23
	v_pk_add_f32 v[126:127], v[126:127], v[198:199]
	v_cvt_pk_bf16_f32 v132, v120, v121
	v_cvt_pk_bf16_f32 v133, v122, v123
	v_cvt_pk_bf16_f32 v134, v124, v125
	v_cvt_pk_bf16_f32 v135, v126, v127
	s_mov_b32 s58, 0x58000
	v_lshl_add_u64 v[200:201], v[188:189], 0, s[58:59]
	global_store_dwordx4 v[200:201], v[132:135], off offset:256 sc1
	s_branch .Lmepi_done
.Lmepi_z0:
	global_load_dwordx4 v[128:131], v[192:193], off nt
	global_load_dwordx4 v[132:135], v[192:193], off offset:256 nt
	s_mov_b32 s58, 0x20000
	v_lshl_add_u64 v[194:195], v[192:193], 0, s[58:59]
	global_load_dwordx4 v[136:139], v[194:195], off nt
	global_load_dwordx4 v[140:143], v[194:195], off offset:256 nt
	s_mov_b32 s58, 0x40000
	v_lshl_add_u64 v[196:197], v[192:193], 0, s[58:59]
	global_load_dwordx4 v[144:147], v[196:197], off nt
	global_load_dwordx4 v[148:151], v[196:197], off offset:256 nt
	s_mov_b32 s58, 0x60000
	v_lshl_add_u64 v[198:199], v[192:193], 0, s[58:59]
	global_load_dwordx4 v[152:155], v[198:199], off nt
	global_load_dwordx4 v[156:159], v[198:199], off offset:256 nt
	s_mov_b32 s58, 0x100000
	v_lshl_add_u64 v[200:201], v[192:193], 0, s[58:59]
	global_load_dwordx4 v[168:171], v[200:201], off nt
	global_load_dwordx4 v[176:179], v[200:201], off offset:256 nt
	s_waitcnt vmcnt(9)
	v_lshlrev_b32_e32 v202, 16, v128
	v_and_b32_e32 v203, 0xffff0000, v128
	v_pk_mul_f32 v[0:1], v[0:1], v[202:203]
	v_lshlrev_b32_e32 v194, 16, v129
	v_and_b32_e32 v195, 0xffff0000, v129
	v_pk_mul_f32 v[2:3], v[2:3], v[194:195]
	v_lshlrev_b32_e32 v196, 16, v130
	v_and_b32_e32 v197, 0xffff0000, v130
	v_pk_mul_f32 v[4:5], v[4:5], v[196:197]
	v_lshlrev_b32_e32 v198, 16, v131
	v_and_b32_e32 v199, 0xffff0000, v131
	v_pk_mul_f32 v[6:7], v[6:7], v[198:199]
	v_cvt_pk_bf16_f32 v204, v0, v1
	v_cvt_pk_bf16_f32 v205, v2, v3
	v_cvt_pk_bf16_f32 v206, v4, v5
	v_cvt_pk_bf16_f32 v207, v6, v7
	s_waitcnt vmcnt(8)
	v_lshlrev_b32_e32 v200, 16, v132
	v_and_b32_e32 v201, 0xffff0000, v132
	v_pk_mul_f32 v[8:9], v[8:9], v[200:201]
	v_lshlrev_b32_e32 v202, 16, v133
	v_and_b32_e32 v203, 0xffff0000, v133
	v_pk_mul_f32 v[10:11], v[10:11], v[202:203]
	v_lshlrev_b32_e32 v194, 16, v134
	v_and_b32_e32 v195, 0xffff0000, v134
	v_pk_mul_f32 v[12:13], v[12:13], v[194:195]
	v_lshlrev_b32_e32 v196, 16, v135
	v_and_b32_e32 v197, 0xffff0000, v135
	v_pk_mul_f32 v[14:15], v[14:15], v[196:197]
	v_cvt_pk_bf16_f32 v208, v8, v9
	v_cvt_pk_bf16_f32 v209, v10, v11
	v_cvt_pk_bf16_f32 v210, v12, v13
	v_cvt_pk_bf16_f32 v211, v14, v15
	s_mov_b32 s58, 0x120000
	v_lshl_add_u64 v[198:199], v[192:193], 0, s[58:59]
	global_load_dwordx4 v[180:183], v[198:199], off nt
	global_load_dwordx4 v[0:3], v[198:199], off offset:256 nt
	s_mov_b32 s58, 0x140000
	v_lshl_add_u64 v[200:201], v[192:193], 0, s[58:59]
	global_load_dwordx4 v[4:7], v[200:201], off nt
	global_load_dwordx4 v[128:131], v[200:201], off offset:256 nt
	s_mov_b32 s58, 0x160000
	v_lshl_add_u64 v[202:203], v[192:193], 0, s[58:59]
	global_load_dwordx4 v[8:11], v[202:203], off nt
	global_load_dwordx4 v[12:15], v[202:203], off offset:256 nt
	s_waitcnt vmcnt(13)
	v_lshlrev_b32_e32 v194, 16, v136
	v_and_b32_e32 v195, 0xffff0000, v136
	v_pk_mul_f32 v[16:17], v[16:17], v[194:195]
	v_lshlrev_b32_e32 v196, 16, v137
	v_and_b32_e32 v197, 0xffff0000, v137
	v_pk_mul_f32 v[18:19], v[18:19], v[196:197]
	v_lshlrev_b32_e32 v198, 16, v138
	v_and_b32_e32 v199, 0xffff0000, v138
	v_pk_mul_f32 v[20:21], v[20:21], v[198:199]
	v_lshlrev_b32_e32 v200, 16, v139
	v_and_b32_e32 v201, 0xffff0000, v139
	v_pk_mul_f32 v[22:23], v[22:23], v[200:201]
	v_cvt_pk_bf16_f32 v212, v16, v17
	v_cvt_pk_bf16_f32 v213, v18, v19
	v_cvt_pk_bf16_f32 v214, v20, v21
	v_cvt_pk_bf16_f32 v215, v22, v23
	s_waitcnt vmcnt(12)
	v_lshlrev_b32_e32 v202, 16, v140
	v_and_b32_e32 v203, 0xffff0000, v140
	v_pk_mul_f32 v[24:25], v[24:25], v[202:203]
	v_lshlrev_b32_e32 v194, 16, v141
	v_and_b32_e32 v195, 0xffff0000, v141
	v_pk_mul_f32 v[26:27], v[26:27], v[194:195]
	v_lshlrev_b32_e32 v196, 16, v142
	v_and_b32_e32 v197, 0xffff0000, v142
	v_pk_mul_f32 v[28:29], v[28:29], v[196:197]
	v_lshlrev_b32_e32 v198, 16, v143
	v_and_b32_e32 v199, 0xffff0000, v143
	v_pk_mul_f32 v[30:31], v[30:31], v[198:199]
	v_cvt_pk_bf16_f32 v216, v24, v25
	v_cvt_pk_bf16_f32 v217, v26, v27
	v_cvt_pk_bf16_f32 v218, v28, v29
	v_cvt_pk_bf16_f32 v219, v30, v31
	s_waitcnt vmcnt(11)
	v_lshlrev_b32_e32 v200, 16, v144
	v_and_b32_e32 v201, 0xffff0000, v144
	v_pk_mul_f32 v[32:33], v[32:33], v[200:201]
	v_lshlrev_b32_e32 v202, 16, v145
	v_and_b32_e32 v203, 0xffff0000, v145
	v_pk_mul_f32 v[34:35], v[34:35], v[202:203]
	v_lshlrev_b32_e32 v194, 16, v146
	v_and_b32_e32 v195, 0xffff0000, v146
	v_pk_mul_f32 v[36:37], v[36:37], v[194:195]
	v_lshlrev_b32_e32 v196, 16, v147
	v_and_b32_e32 v197, 0xffff0000, v147
	v_pk_mul_f32 v[38:39], v[38:39], v[196:197]
	v_cvt_pk_bf16_f32 v220, v32, v33
	v_cvt_pk_bf16_f32 v221, v34, v35
	v_cvt_pk_bf16_f32 v222, v36, v37
	v_cvt_pk_bf16_f32 v223, v38, v39
	s_waitcnt vmcnt(10)
	v_lshlrev_b32_e32 v198, 16, v148
	v_and_b32_e32 v199, 0xffff0000, v148
	v_pk_mul_f32 v[40:41], v[40:41], v[198:199]
	v_lshlrev_b32_e32 v200, 16, v149
	v_and_b32_e32 v201, 0xffff0000, v149
	v_pk_mul_f32 v[42:43], v[42:43], v[200:201]
	v_lshlrev_b32_e32 v202, 16, v150
	v_and_b32_e32 v203, 0xffff0000, v150
	v_pk_mul_f32 v[44:45], v[44:45], v[202:203]
	v_lshlrev_b32_e32 v194, 16, v151
	v_and_b32_e32 v195, 0xffff0000, v151
	v_pk_mul_f32 v[46:47], v[46:47], v[194:195]
	v_cvt_pk_bf16_f32 v224, v40, v41
	v_cvt_pk_bf16_f32 v225, v42, v43
	v_cvt_pk_bf16_f32 v226, v44, v45
	v_cvt_pk_bf16_f32 v227, v46, v47
	s_waitcnt vmcnt(9)
	v_lshlrev_b32_e32 v196, 16, v152
	v_and_b32_e32 v197, 0xffff0000, v152
	v_pk_mul_f32 v[48:49], v[48:49], v[196:197]
	v_lshlrev_b32_e32 v198, 16, v153
	v_and_b32_e32 v199, 0xffff0000, v153
	v_pk_mul_f32 v[50:51], v[50:51], v[198:199]
	v_lshlrev_b32_e32 v200, 16, v154
	v_and_b32_e32 v201, 0xffff0000, v154
	v_pk_mul_f32 v[52:53], v[52:53], v[200:201]
	v_lshlrev_b32_e32 v202, 16, v155
	v_and_b32_e32 v203, 0xffff0000, v155
	v_pk_mul_f32 v[54:55], v[54:55], v[202:203]
	v_cvt_pk_bf16_f32 v228, v48, v49
	v_cvt_pk_bf16_f32 v229, v50, v51
	v_cvt_pk_bf16_f32 v230, v52, v53
	v_cvt_pk_bf16_f32 v231, v54, v55
	s_waitcnt vmcnt(8)
	v_lshlrev_b32_e32 v194, 16, v156
	v_and_b32_e32 v195, 0xffff0000, v156
	v_pk_mul_f32 v[56:57], v[56:57], v[194:195]
	v_lshlrev_b32_e32 v196, 16, v157
	v_and_b32_e32 v197, 0xffff0000, v157
	v_pk_mul_f32 v[58:59], v[58:59], v[196:197]
	v_lshlrev_b32_e32 v198, 16, v158
	v_and_b32_e32 v199, 0xffff0000, v158
	v_pk_mul_f32 v[60:61], v[60:61], v[198:199]
	v_lshlrev_b32_e32 v200, 16, v159
	v_and_b32_e32 v201, 0xffff0000, v159
	v_pk_mul_f32 v[62:63], v[62:63], v[200:201]
	v_cvt_pk_bf16_f32 v236, v56, v57
	v_cvt_pk_bf16_f32 v237, v58, v59
	v_cvt_pk_bf16_f32 v238, v60, v61
	v_cvt_pk_bf16_f32 v239, v62, v63
	s_waitcnt vmcnt(7)
	v_lshlrev_b32_e32 v202, 16, v168
	v_and_b32_e32 v203, 0xffff0000, v168
	v_pk_mul_f32 v[64:65], v[64:65], v[202:203]
	v_lshlrev_b32_e32 v194, 16, v169
	v_and_b32_e32 v195, 0xffff0000, v169
	v_pk_mul_f32 v[66:67], v[66:67], v[194:195]
	v_lshlrev_b32_e32 v196, 16, v170
	v_and_b32_e32 v197, 0xffff0000, v170
	v_pk_mul_f32 v[68:69], v[68:69], v[196:197]
	v_lshlrev_b32_e32 v198, 16, v171
	v_and_b32_e32 v199, 0xffff0000, v171
	v_pk_mul_f32 v[70:71], v[70:71], v[198:199]
	v_cvt_pk_bf16_f32 v240, v64, v65
	v_cvt_pk_bf16_f32 v241, v66, v67
	v_cvt_pk_bf16_f32 v242, v68, v69
	v_cvt_pk_bf16_f32 v243, v70, v71
	s_waitcnt vmcnt(6)
	v_lshlrev_b32_e32 v200, 16, v176
	v_and_b32_e32 v201, 0xffff0000, v176
	v_pk_mul_f32 v[72:73], v[72:73], v[200:201]
	v_lshlrev_b32_e32 v202, 16, v177
	v_and_b32_e32 v203, 0xffff0000, v177
	v_pk_mul_f32 v[74:75], v[74:75], v[202:203]
	v_lshlrev_b32_e32 v194, 16, v178
	v_and_b32_e32 v195, 0xffff0000, v178
	v_pk_mul_f32 v[76:77], v[76:77], v[194:195]
	v_lshlrev_b32_e32 v196, 16, v179
	v_and_b32_e32 v197, 0xffff0000, v179
	v_pk_mul_f32 v[78:79], v[78:79], v[196:197]
	v_cvt_pk_bf16_f32 v244, v72, v73
	v_cvt_pk_bf16_f32 v245, v74, v75
	v_cvt_pk_bf16_f32 v246, v76, v77
	v_cvt_pk_bf16_f32 v247, v78, v79
	s_waitcnt vmcnt(5)
	v_lshlrev_b32_e32 v198, 16, v180
	v_and_b32_e32 v199, 0xffff0000, v180
	v_pk_mul_f32 v[80:81], v[80:81], v[198:199]
	v_lshlrev_b32_e32 v200, 16, v181
	v_and_b32_e32 v201, 0xffff0000, v181
	v_pk_mul_f32 v[82:83], v[82:83], v[200:201]
	v_lshlrev_b32_e32 v202, 16, v182
	v_and_b32_e32 v203, 0xffff0000, v182
	v_pk_mul_f32 v[84:85], v[84:85], v[202:203]
	v_lshlrev_b32_e32 v194, 16, v183
	v_and_b32_e32 v195, 0xffff0000, v183
	v_pk_mul_f32 v[86:87], v[86:87], v[194:195]
	v_cvt_pk_bf16_f32 v248, v80, v81
	v_cvt_pk_bf16_f32 v249, v82, v83
	v_cvt_pk_bf16_f32 v250, v84, v85
	v_cvt_pk_bf16_f32 v251, v86, v87
	s_waitcnt vmcnt(4)
	v_lshlrev_b32_e32 v196, 16, v0
	v_and_b32_e32 v197, 0xffff0000, v0
	v_pk_mul_f32 v[88:89], v[88:89], v[196:197]
	v_lshlrev_b32_e32 v198, 16, v1
	v_and_b32_e32 v199, 0xffff0000, v1
	v_pk_mul_f32 v[90:91], v[90:91], v[198:199]
	v_lshlrev_b32_e32 v200, 16, v2
	v_and_b32_e32 v201, 0xffff0000, v2
	v_pk_mul_f32 v[92:93], v[92:93], v[200:201]
	v_lshlrev_b32_e32 v202, 16, v3
	v_and_b32_e32 v203, 0xffff0000, v3
	v_pk_mul_f32 v[94:95], v[94:95], v[202:203]
	v_cvt_pk_bf16_f32 v161, v88, v89
	v_cvt_pk_bf16_f32 v163, v90, v91
	v_cvt_pk_bf16_f32 v165, v92, v93
	v_cvt_pk_bf16_f32 v166, v94, v95
	s_waitcnt vmcnt(3)
	v_lshlrev_b32_e32 v194, 16, v4
	v_and_b32_e32 v195, 0xffff0000, v4
	v_pk_mul_f32 v[96:97], v[96:97], v[194:195]
	v_lshlrev_b32_e32 v196, 16, v5
	v_and_b32_e32 v197, 0xffff0000, v5
	v_pk_mul_f32 v[98:99], v[98:99], v[196:197]
	v_lshlrev_b32_e32 v198, 16, v6
	v_and_b32_e32 v199, 0xffff0000, v6
	v_pk_mul_f32 v[100:101], v[100:101], v[198:199]
	v_lshlrev_b32_e32 v200, 16, v7
	v_and_b32_e32 v201, 0xffff0000, v7
	v_pk_mul_f32 v[102:103], v[102:103], v[200:201]
	v_cvt_pk_bf16_f32 v167, v96, v97
	v_cvt_pk_bf16_f32 v172, v98, v99
	v_cvt_pk_bf16_f32 v173, v100, v101
	v_cvt_pk_bf16_f32 v234, v102, v103
	s_waitcnt vmcnt(2)
	v_lshlrev_b32_e32 v202, 16, v128
	v_and_b32_e32 v203, 0xffff0000, v128
	v_pk_mul_f32 v[104:105], v[104:105], v[202:203]
	v_lshlrev_b32_e32 v194, 16, v129
	v_and_b32_e32 v195, 0xffff0000, v129
	v_pk_mul_f32 v[106:107], v[106:107], v[194:195]
	v_lshlrev_b32_e32 v196, 16, v130
	v_and_b32_e32 v197, 0xffff0000, v130
	v_pk_mul_f32 v[108:109], v[108:109], v[196:197]
	v_lshlrev_b32_e32 v198, 16, v131
	v_and_b32_e32 v199, 0xffff0000, v131
	v_pk_mul_f32 v[110:111], v[110:111], v[198:199]
	v_cvt_pk_bf16_f32 v128, v104, v105
	v_cvt_pk_bf16_f32 v129, v106, v107
	v_cvt_pk_bf16_f32 v130, v108, v109
	v_cvt_pk_bf16_f32 v131, v110, v111
	ds_write_b128 v191, v[128:131] offset:0
	s_waitcnt lgkmcnt(0)
	s_waitcnt vmcnt(1)
	v_lshlrev_b32_e32 v200, 16, v8
	v_and_b32_e32 v201, 0xffff0000, v8
	v_pk_mul_f32 v[112:113], v[112:113], v[200:201]
	v_lshlrev_b32_e32 v202, 16, v9
	v_and_b32_e32 v203, 0xffff0000, v9
	v_pk_mul_f32 v[114:115], v[114:115], v[202:203]
	v_lshlrev_b32_e32 v194, 16, v10
	v_and_b32_e32 v195, 0xffff0000, v10
	v_pk_mul_f32 v[116:117], v[116:117], v[194:195]
	v_lshlrev_b32_e32 v196, 16, v11
	v_and_b32_e32 v197, 0xffff0000, v11
	v_pk_mul_f32 v[118:119], v[118:119], v[196:197]
	v_cvt_pk_bf16_f32 v8, v112, v113
	v_cvt_pk_bf16_f32 v9, v114, v115
	v_cvt_pk_bf16_f32 v10, v116, v117
	v_cvt_pk_bf16_f32 v11, v118, v119
	ds_write_b128 v191, v[8:11] offset:8192
	s_waitcnt lgkmcnt(0)
	s_waitcnt vmcnt(0)
	v_lshlrev_b32_e32 v198, 16, v12
	v_and_b32_e32 v199, 0xffff0000, v12
	v_pk_mul_f32 v[120:121], v[120:121], v[198:199]
	v_lshlrev_b32_e32 v200, 16, v13
	v_and_b32_e32 v201, 0xffff0000, v13
	v_pk_mul_f32 v[122:123], v[122:123], v[200:201]
	v_lshlrev_b32_e32 v202, 16, v14
	v_and_b32_e32 v203, 0xffff0000, v14
	v_pk_mul_f32 v[124:125], v[124:125], v[202:203]
	v_lshlrev_b32_e32 v194, 16, v15
	v_and_b32_e32 v195, 0xffff0000, v15
	v_pk_mul_f32 v[126:127], v[126:127], v[194:195]
	v_cvt_pk_bf16_f32 v12, v120, v121
	v_cvt_pk_bf16_f32 v13, v122, v123
	v_cvt_pk_bf16_f32 v14, v124, v125
	v_cvt_pk_bf16_f32 v15, v126, v127
	ds_write_b128 v191, v[12:15] offset:16384
	s_waitcnt lgkmcnt(0)
